# adds SGU head-loop exact gelu(u) waits, SGU stats first wait vmcnt(15), and counted wait ladders for the G3+G4 gate-load bursts (mid + epilogue)
# speedup vs baseline: 1.0038x; 1.0038x over previous
; __device__ __forceinline__ float bf_lo(unsigned u) { return __uint_as_float(u << 16); }
; __device__ __forceinline__ float bf_hi(unsigned u) { return __uint_as_float(u & 0xffff0000u); }
; __device__ __forceinline__ void sgu_pool_chunk(KArgs A, int l, int chunk, LAS unsigned char* lds) {
;     ...
;     for (int i0 = 0; i0 < 16; i0 += 8) {
;         u32x4 x0[8], x1[8];
; #pragma unroll
;         for (int i = 0; i < 8; ++i) { const bf16_t* row = gv + (size_t)(t0 + w * 16 + i0 + i) * D_; x0[i] = *(const u32x4*)(row + lane * 8); x1[i] = *(const u32x4*)(row + 512 + lane * 8); }
; #pragma unroll
;         for (int i = 0; i < 8; ++i) {
;             float f[16] = {bf_lo(x0[i].x), bf_hi(x0[i].x), bf_lo(x0[i].y), bf_hi(x0[i].y), bf_lo(x0[i].z), bf_hi(x0[i].z), bf_lo(x0[i].w), bf_hi(x0[i].w),
;                            bf_lo(x1[i].x), bf_hi(x1[i].x), bf_lo(x1[i].y), bf_hi(x1[i].y), bf_lo(x1[i].z), bf_hi(x1[i].z), bf_lo(x1[i].w), bf_hi(x1[i].w)};
;             float s = 0.f;
; #pragma unroll
;             for (int j = 0; j < 16; ++j) s += f[j];
;             const float mean = wave_sum(s) * (1.f / D_); float s2 = 0.f;
; #pragma unroll
;             for (int j = 0; j < 16; ++j) { const float d = f[j] - mean; s2 += d * d; }
;             const float rstd = 1.f / sqrtf(wave_sum(s2) * (1.f / D_) + LN_EPS_);
;             if (lane == 0) { st_mean[w * 16 + i0 + i] = mean; st_rstd[w * 16 + i0 + i] = rstd; }
;         }
.LBB0_330:
	s_or_b32 s0, s8, s25
	s_ashr_i32 s1, s0, 31
	s_lshl_b64 s[26:27], s[0:1], 11
	v_lshl_add_u64 v[0:1], v[66:67], 0, s[26:27]
	global_load_dwordx4 v[60:63], v[0:1], off
	global_load_dwordx4 v[56:59], v[0:1], off offset:1024
	s_or_b32 s26, s0, 1
	s_ashr_i32 s27, s26, 31
	s_lshl_b64 s[26:27], s[26:27], 11
	v_lshl_add_u64 v[0:1], v[66:67], 0, s[26:27]
	s_or_b32 s26, s0, 2
	s_ashr_i32 s27, s26, 31
	s_lshl_b64 s[26:27], s[26:27], 11
	global_load_dwordx4 v[52:55], v[0:1], off
	global_load_dwordx4 v[48:51], v[0:1], off offset:1024
	v_lshl_add_u64 v[0:1], v[66:67], 0, s[26:27]
	s_or_b32 s26, s0, 3
	s_ashr_i32 s27, s26, 31
	s_lshl_b64 s[26:27], s[26:27], 11
	global_load_dwordx4 v[44:47], v[0:1], off
	global_load_dwordx4 v[40:43], v[0:1], off offset:1024
	v_lshl_add_u64 v[0:1], v[66:67], 0, s[26:27]
	s_or_b32 s26, s0, 4
	s_ashr_i32 s27, s26, 31
	s_lshl_b64 s[26:27], s[26:27], 11
	global_load_dwordx4 v[36:39], v[0:1], off
	global_load_dwordx4 v[32:35], v[0:1], off offset:1024
	v_lshl_add_u64 v[0:1], v[66:67], 0, s[26:27]
	s_or_b32 s26, s0, 5
	s_ashr_i32 s27, s26, 31
	s_lshl_b64 s[26:27], s[26:27], 11
	global_load_dwordx4 v[28:31], v[0:1], off
	global_load_dwordx4 v[24:27], v[0:1], off offset:1024
	v_lshl_add_u64 v[0:1], v[66:67], 0, s[26:27]
	s_or_b32 s26, s0, 6
	s_ashr_i32 s27, s26, 31
	s_or_b32 s0, s0, 7
	s_lshl_b64 s[26:27], s[26:27], 11
	s_ashr_i32 s1, s0, 31
	global_load_dwordx4 v[20:23], v[0:1], off
	global_load_dwordx4 v[16:19], v[0:1], off offset:1024
	v_lshl_add_u64 v[0:1], v[66:67], 0, s[26:27]
	s_lshl_b64 s[0:1], s[0:1], 11
	global_load_dwordx4 v[12:15], v[0:1], off
	global_load_dwordx4 v[8:11], v[0:1], off offset:1024
	v_lshl_add_u64 v[0:1], v[66:67], 0, s[0:1]
	global_load_dwordx4 v[4:7], v[0:1], off
	s_waitcnt lgkmcnt(0)
	global_load_dwordx4 v[0:3], v[0:1], off offset:1024
	s_or_b32 s19, s8, s5
	s_waitcnt vmcnt(15)
	v_lshlrev_b32_e32 v74, 16, v60
	v_and_b32_e32 v60, 0xffff0000, v60
	s_waitcnt vmcnt(14)
	v_lshlrev_b32_e32 v78, 16, v56
	v_and_b32_e32 v79, 0xffff0000, v56
	v_add_f32_e32 v56, 0, v74
	v_lshlrev_b32_e32 v75, 16, v61
	v_add_f32_e32 v56, v56, v60
	v_and_b32_e32 v61, 0xffff0000, v61
	v_add_f32_e32 v56, v56, v75
	v_lshlrev_b32_e32 v76, 16, v62
	v_add_f32_e32 v56, v56, v61
	v_and_b32_e32 v62, 0xffff0000, v62
	v_add_f32_e32 v56, v56, v76
	v_lshlrev_b32_e32 v77, 16, v63
	v_add_f32_e32 v56, v56, v62
	v_and_b32_e32 v63, 0xffff0000, v63
	v_add_f32_e32 v56, v56, v77
	v_add_f32_e32 v56, v56, v63
	v_add_f32_e32 v56, v56, v78
	v_lshlrev_b32_e32 v80, 16, v57
	v_add_f32_e32 v56, v56, v79
	v_and_b32_e32 v57, 0xffff0000, v57
	v_add_f32_e32 v56, v56, v80
	v_lshlrev_b32_e32 v81, 16, v58
	v_add_f32_e32 v56, v56, v57
	v_and_b32_e32 v58, 0xffff0000, v58
	v_add_f32_e32 v56, v56, v81
	v_lshlrev_b32_e32 v82, 16, v59
	v_add_f32_e32 v56, v56, v58
	v_and_b32_e32 v59, 0xffff0000, v59
	v_add_f32_e32 v56, v56, v82
	v_add_f32_e32 v56, v56, v59
	s_waitcnt lgkmcnt(0)
	s_nop 1
	v_add_f32_dpp v56, v56, v56 quad_perm:[1,0,3,2] row_mask:0xf bank_mask:0xf
	s_waitcnt lgkmcnt(0)
	s_nop 1
	v_add_f32_dpp v56, v56, v56 quad_perm:[2,3,0,1] row_mask:0xf bank_mask:0xf
	s_waitcnt lgkmcnt(0)
	s_nop 1
	v_add_f32_dpp v56, v56, v56 row_half_mirror row_mask:0xf bank_mask:0xf
	s_waitcnt lgkmcnt(0)
	s_nop 1
	v_add_f32_dpp v56, v56, v56 row_mirror row_mask:0xf bank_mask:0xf
	s_waitcnt lgkmcnt(0)
	v_mov_b32_e32 v83, v56
	s_nop 1
	v_permlane16_swap_b32 v56, v83
	v_add_f32_e32 v56, v56, v83
	s_waitcnt lgkmcnt(0)
	v_mov_b32_e32 v83, v56
	s_nop 1
	v_permlane32_swap_b32 v56, v83
	v_add_f32_e32 v56, v56, v83
	v_fmac_f32_e32 v60, 0xba800000, v56
	v_fmac_f32_e32 v74, 0xba800000, v56
	v_mul_f32_e32 v60, v60, v60
	v_fmac_f32_e32 v60, v74, v74
	v_fmac_f32_e32 v75, 0xba800000, v56
	v_fmac_f32_e32 v60, v75, v75
	v_fmac_f32_e32 v61, 0xba800000, v56
	v_fmac_f32_e32 v60, v61, v61
	v_fmac_f32_e32 v76, 0xba800000, v56
	v_fmac_f32_e32 v60, v76, v76
	v_fmac_f32_e32 v62, 0xba800000, v56
	v_fmac_f32_e32 v60, v62, v62
	v_fmac_f32_e32 v77, 0xba800000, v56
	v_fmac_f32_e32 v60, v77, v77
	v_fmac_f32_e32 v63, 0xba800000, v56
	v_fmac_f32_e32 v60, v63, v63
	v_fmac_f32_e32 v78, 0xba800000, v56
	v_fmac_f32_e32 v60, v78, v78
	v_fmac_f32_e32 v79, 0xba800000, v56
	v_fmac_f32_e32 v60, v79, v79
	v_fmac_f32_e32 v80, 0xba800000, v56
	v_fmac_f32_e32 v60, v80, v80
	v_fmac_f32_e32 v57, 0xba800000, v56
	v_fmac_f32_e32 v60, v57, v57
	v_fmac_f32_e32 v81, 0xba800000, v56
	v_fmac_f32_e32 v60, v81, v81
	v_fmac_f32_e32 v58, 0xba800000, v56
	v_fmac_f32_e32 v60, v58, v58
	v_fmac_f32_e32 v82, 0xba800000, v56
	v_fmac_f32_e32 v60, v82, v82
	v_fmac_f32_e32 v59, 0xba800000, v56
	v_fmac_f32_e32 v60, v59, v59
	s_waitcnt lgkmcnt(0)
	s_nop 1
	v_add_f32_dpp v57, v60, v60 quad_perm:[1,0,3,2] row_mask:0xf bank_mask:0xf
	s_waitcnt lgkmcnt(0)
	s_nop 1
	v_add_f32_dpp v57, v57, v57 quad_perm:[2,3,0,1] row_mask:0xf bank_mask:0xf
	s_waitcnt lgkmcnt(0)
	s_nop 1
	v_add_f32_dpp v57, v57, v57 row_half_mirror row_mask:0xf bank_mask:0xf
	s_waitcnt lgkmcnt(0)
	s_nop 1
	v_add_f32_dpp v57, v57, v57 row_mirror row_mask:0xf bank_mask:0xf
	s_waitcnt lgkmcnt(0)
	v_mov_b32_e32 v58, v57
	s_nop 1
	v_permlane16_swap_b32 v57, v58
	v_add_f32_e32 v57, v57, v58
	ds_bpermute_b32 v58, v73, v57
	s_and_saveexec_b64 s[0:1], s[6:7]
	s_cbranch_execz .LBB0_332
	s_waitcnt lgkmcnt(0)
	v_add_f32_e32 v57, v57, v58
	v_fmamk_f32 v57, v57, 0x3a800000, v227
	v_mul_f32_e32 v58, 0x4f800000, v57
	v_cmp_gt_f32_e32 vcc, s47, v57
	v_mul_f32_e32 v56, 0x3a800000, v56
	s_nop 0
	v_cndmask_b32_e32 v57, v57, v58, vcc
	v_sqrt_f32_e32 v58, v57
	s_nop 0
	v_add_u32_e32 v59, -1, v58
	v_fma_f32 v61, -v59, v58, v57
	v_add_u32_e32 v60, 1, v58
	v_cmp_ge_f32_e64 s[8:9], 0, v61
	s_nop 1
	v_cndmask_b32_e64 v59, v58, v59, s[8:9]
	v_fma_f32 v58, -v60, v58, v57
	v_cmp_lt_f32_e64 s[8:9], 0, v58
	s_nop 1
	v_cndmask_b32_e64 v58, v59, v60, s[8:9]
	v_mul_f32_e32 v59, 0x37800000, v58
	v_cndmask_b32_e32 v58, v58, v59, vcc
	v_cmp_class_f32_e32 vcc, v57, v228
	s_nop 1
	v_cndmask_b32_e32 v57, v58, v57, vcc
	v_div_scale_f32 v58, s[8:9], v57, v57, 1.0
	v_rcp_f32_e32 v59, v58
	s_lshl_b32 s8, s19, 2
	s_add_i32 s8, s8, 0
	s_add_i32 s9, s8, 0x11000
	v_fma_f32 v60, -v58, v59, 1.0
	v_fmac_f32_e32 v59, v60, v59
	v_div_scale_f32 v60, vcc, 1.0, v57, 1.0
	v_mul_f32_e32 v61, v60, v59
	v_fma_f32 v62, -v58, v61, v60
	v_fmac_f32_e32 v61, v62, v59
	v_fma_f32 v58, -v58, v61, v60
	v_div_fmas_f32 v58, v58, v59, v61
	v_div_fixup_f32 v57, v58, v57, 1.0
	v_mov_b32_e32 v58, s9
	s_add_i32 s8, s8, 0x11200
	ds_write_b32 v58, v56
	v_mov_b32_e32 v56, s8
	ds_write_b32 v56, v57

; #define LAS __attribute__((address_space(3)))
; __device__ __forceinline__ unsigned cvt_pk_bf16(float lo, float hi) { unsigned r; asm volatile("v_cvt_pk_bf16_f32 %0, %1, %2" : "=v"(r) : "v"(lo), "v"(hi)); return r; }
; __device__ __forceinline__ float bf_lo(unsigned u) { return __uint_as_float(u << 16); }
; __device__ __forceinline__ float bf_hi(unsigned u) { return __uint_as_float(u & 0xffff0000u); }
; __device__ __forceinline__ void sgu_pool_chunk(KArgs A, int l, int chunk, LAS unsigned char* lds) {
;     ...
;     for (int h = 0; h < 8; ++h) {
;         const LAS bf16_t* Vt = (const LAS bf16_t*)(lds + (h & 1) * (128 * 272));
; #pragma unroll
;         for (int ks = 0; ks < 4; ++ks) bfr[ks] = bfn[ks];
;         const float bias = sbL[h * 128 + pl];
;         u32x4 uu[4];
; #pragma unroll
;         for (int m = 0; m < 4; ++m) uu[m] = __builtin_nontemporal_load((const u32x4*)(gu + (size_t)(t0 + pl) * D_ + h * 128 + m * 32 + (lane >> 4) * 8));
;         if (h + 1 < 8) { SGU_STAGE(h + 1, bfn); if (h + 2 < 8) SGU_LOAD(h + 2); }
; #pragma unroll
;         for (int m = 0; m < 4; ++m) {
;             f32x4 acc0 = (f32x4){0.f, 0.f, 0.f, 0.f}, acc1 = (f32x4){0.f, 0.f, 0.f, 0.f};
;             const int arow = m * 32 + ((lane & 15) >> 2) * 8 + (lane & 3);
; #pragma unroll
;             for (int ks = 0; ks < 4; ++ks) { const int ch = (ks * 4 + (lane >> 4)) ^ ((arow >> 3) & 15);
;                 const bf16x8 a0 = *(const LAS bf16x8*)(Vt + arow * 136 + ch * 8), a1 = *(const LAS bf16x8*)(Vt + (arow + 4) * 136 + ch * 8);
;                 acc0 = __builtin_amdgcn_mfma_f32_16x16x32_bf16(a0, bfr[ks], acc0, 0, 0, 0); acc1 = __builtin_amdgcn_mfma_f32_16x16x32_bf16(a1, bfr[ks], acc1, 0, 0, 0); }
;             const u32x4 u4 = uu[m];
;             u32x4 r; r.x = cvt_pk_bf16(bf_lo(u4.x) * (acc0[0] + bias), bf_hi(u4.x) * (acc0[1] + bias)); r.y = cvt_pk_bf16(bf_lo(u4.y) * (acc0[2] + bias), bf_hi(u4.y) * (acc0[3] + bias));
;             r.z = cvt_pk_bf16(bf_lo(u4.z) * (acc1[0] + bias), bf_hi(u4.z) * (acc1[1] + bias)); r.w = cvt_pk_bf16(bf_lo(u4.w) * (acc1[2] + bias), bf_hi(u4.w) * (acc1[3] + bias));
;             *(u32x4*)(yb + (size_t)(t0 + pl) * LDAB + h * 128 + m * 32 + (lane >> 4) * 8) = r;
;         }
.LBB0_348:
	s_bitcmp1_b32 s4, 0
	s_cselect_b32 s4, 0x8800, 0
	v_add_u32_e32 v121, s4, v118
	v_lshl_add_u32 v126, v103, 1, v121
	v_lshl_add_u32 v134, v104, 1, v121
	ds_read_b128 v[122:125], v126
	ds_read_b128 v[126:129], v126 offset:1088
	ds_read_b128 v[130:133], v134
	ds_read_b128 v[134:137], v134 offset:1088
	s_waitcnt lgkmcnt(3)
	v_mfma_f32_16x16x32_bf16 v[122:125], v[122:125], v[12:15], 0
	v_lshl_add_u32 v138, v105, 1, v121
	s_waitcnt vmcnt(11)
	s_cmpk_le_u32 s0, 0xa00
	s_cbranch_scc1 .Lsgu_uu_1
	s_waitcnt vmcnt(3)
.Lsgu_uu_1:
	v_lshlrev_b32_e32 v139, 16, v60
	v_and_b32_e32 v60, 0xffff0000, v60
	s_waitcnt lgkmcnt(2)
	v_mfma_f32_16x16x32_bf16 v[126:129], v[126:129], v[12:15], 0
	v_lshlrev_b32_e32 v140, 16, v61
	v_and_b32_e32 v61, 0xffff0000, v61
	s_mov_b32 s4, 0x30f00000
	s_waitcnt lgkmcnt(1)
	v_mfma_f32_16x16x32_bf16 v[122:125], v[130:133], v[8:11], v[122:125]
	ds_read_b128 v[130:133], v138
	s_addk_i32 s0, 0x200
	v_lshl_add_u64 v[82:83], v[82:83], 0, s[70:71]
	s_waitcnt lgkmcnt(1)
	v_mfma_f32_16x16x32_bf16 v[126:129], v[134:137], v[8:11], v[126:129]
	ds_read_b128 v[134:137], v138 offset:1088
	v_lshl_add_u32 v138, v106, 1, v121
	v_lshl_add_u64 v[84:85], v[84:85], 0, s[70:71]
	s_waitcnt lgkmcnt(1)
	v_mfma_f32_16x16x32_bf16 v[122:125], v[130:133], v[4:7], v[122:125]
	ds_read_b128 v[130:133], v138
	v_lshl_add_u64 v[86:87], v[86:87], 0, s[70:71]
	v_lshl_add_u64 v[88:89], v[88:89], 0, s[70:71]
	s_waitcnt lgkmcnt(1)
	v_mfma_f32_16x16x32_bf16 v[126:129], v[134:137], v[4:7], v[126:129]
	ds_read_b128 v[134:137], v138 offset:1088
	v_lshl_add_u32 v138, v110, 1, v121
	v_lshl_add_u64 v[92:93], v[92:93], 0, s[70:71]
	s_waitcnt lgkmcnt(1)
	v_mfma_f32_16x16x32_bf16 v[122:125], v[130:133], v[0:3], v[122:125]
	s_waitcnt lgkmcnt(0)
	v_mfma_f32_16x16x32_bf16 v[126:129], v[134:137], v[0:3], v[126:129]
	s_nop 4
	v_add_f32_e32 v122, v120, v122
	v_add_f32_e32 v123, v120, v123
	v_add_f32_e32 v124, v120, v124
	v_mul_f32_e32 v122, v122, v139
	v_mul_f32_e32 v60, v123, v60
	v_add_f32_e32 v123, v120, v125
	v_cvt_pk_bf16_f32 v60, v122, v60
	v_mul_f32_e32 v122, v124, v140
	v_mul_f32_e32 v61, v123, v61
	v_cvt_pk_bf16_f32 v61, v122, v61
	v_lshlrev_b32_e32 v122, 16, v62
	v_add_f32_e32 v123, v120, v126
	v_mul_f32_e32 v122, v123, v122
	v_and_b32_e32 v62, 0xffff0000, v62
	v_add_f32_e32 v123, v120, v127
	v_mul_f32_e32 v62, v123, v62
	v_cvt_pk_bf16_f32 v62, v122, v62
	v_lshlrev_b32_e32 v122, 16, v63
	v_add_f32_e32 v123, v120, v128
	v_mul_f32_e32 v122, v123, v122
	v_and_b32_e32 v63, 0xffff0000, v63
	v_add_f32_e32 v123, v120, v129
	v_mul_f32_e32 v63, v123, v63
	v_lshl_add_u32 v126, v107, 1, v121
	v_lshl_add_u32 v134, v108, 1, v121
	v_cvt_pk_bf16_f32 v63, v122, v63
	ds_read_b128 v[122:125], v126 offset:8704
	ds_read_b128 v[126:129], v126 offset:9792
	ds_read_b128 v[130:133], v134 offset:8704
	ds_read_b128 v[134:137], v134 offset:9792
	s_waitcnt lgkmcnt(2)
	v_mfma_f32_16x16x32_bf16 v[126:129], v[126:129], v[12:15], 0
	v_mfma_f32_16x16x32_bf16 v[122:125], v[122:125], v[12:15], 0
	s_waitcnt lgkmcnt(0)
	v_mfma_f32_16x16x32_bf16 v[126:129], v[134:137], v[8:11], v[126:129]
	v_lshl_add_u32 v134, v109, 1, v121
	v_mfma_f32_16x16x32_bf16 v[122:125], v[130:133], v[8:11], v[122:125]
	ds_read_b128 v[130:133], v134 offset:8704
	ds_read_b128 v[134:137], v134 offset:9792
	s_waitcnt lgkmcnt(1)
	v_mfma_f32_16x16x32_bf16 v[122:125], v[130:133], v[4:7], v[122:125]
	ds_read_b128 v[130:133], v138 offset:8704
	s_waitcnt lgkmcnt(1)
	v_mfma_f32_16x16x32_bf16 v[126:129], v[134:137], v[4:7], v[126:129]
	ds_read_b128 v[134:137], v138 offset:9792
	v_lshl_add_u64 v[138:139], s[20:21], 0, v[90:91]
	v_add_co_u32_e32 v138, vcc, s4, v138
	s_waitcnt lgkmcnt(1)
	v_mfma_f32_16x16x32_bf16 v[122:125], v[130:133], v[0:3], v[122:125]
	v_addc_co_u32_e32 v139, vcc, 0, v139, vcc
	global_store_dwordx4 v[138:139], v[60:63], off offset:1024
	v_lshl_add_u32 v130, v112, 1, v121
	s_nop 4
	v_add_f32_e32 v122, v120, v122
	s_waitcnt lgkmcnt(0)
	v_mfma_f32_16x16x32_bf16 v[60:63], v[134:137], v[0:3], v[126:129]
	v_add_f32_e32 v123, v120, v123
	v_lshl_add_u32 v134, v113, 1, v121
	s_mov_b64 s[4:5], 0x8000
	s_waitcnt vmcnt(11)
	s_cmpk_le_u32 s0, 0xc00
	s_cbranch_scc1 .Lsgu_uu_2
	s_waitcnt vmcnt(3)
; #define LAS __attribute__((address_space(3)))
; __device__ __forceinline__ unsigned cvt_pk_bf16(float lo, float hi) { unsigned r; asm volatile("v_cvt_pk_bf16_f32 %0, %1, %2" : "=v"(r) : "v"(lo), "v"(hi)); return r; }
; __device__ __forceinline__ float bf_lo(unsigned u) { return __uint_as_float(u << 16); }
; __device__ __forceinline__ float bf_hi(unsigned u) { return __uint_as_float(u & 0xffff0000u); }
; __device__ __forceinline__ void sgu_pool_chunk(KArgs A, int l, int chunk, LAS unsigned char* lds) {
;     ...
;         for (int m = 0; m < 4; ++m) {
;             f32x4 acc0 = (f32x4){0.f, 0.f, 0.f, 0.f}, acc1 = (f32x4){0.f, 0.f, 0.f, 0.f};
;             const int arow = m * 32 + ((lane & 15) >> 2) * 8 + (lane & 3);
; #pragma unroll
;             for (int ks = 0; ks < 4; ++ks) { const int ch = (ks * 4 + (lane >> 4)) ^ ((arow >> 3) & 15);
;                 const bf16x8 a0 = *(const LAS bf16x8*)(Vt + arow * 136 + ch * 8), a1 = *(const LAS bf16x8*)(Vt + (arow + 4) * 136 + ch * 8);
;                 acc0 = __builtin_amdgcn_mfma_f32_16x16x32_bf16(a0, bfr[ks], acc0, 0, 0, 0); acc1 = __builtin_amdgcn_mfma_f32_16x16x32_bf16(a1, bfr[ks], acc1, 0, 0, 0); }
;             const u32x4 u4 = uu[m];
;             u32x4 r; r.x = cvt_pk_bf16(bf_lo(u4.x) * (acc0[0] + bias), bf_hi(u4.x) * (acc0[1] + bias)); r.y = cvt_pk_bf16(bf_lo(u4.y) * (acc0[2] + bias), bf_hi(u4.y) * (acc0[3] + bias));
;             r.z = cvt_pk_bf16(bf_lo(u4.z) * (acc1[0] + bias), bf_hi(u4.z) * (acc1[1] + bias)); r.w = cvt_pk_bf16(bf_lo(u4.w) * (acc1[2] + bias), bf_hi(u4.w) * (acc1[3] + bias));
;             *(u32x4*)(yb + (size_t)(t0 + pl) * LDAB + h * 128 + m * 32 + (lane >> 4) * 8) = r;
;         }
;         __syncthreads();
;     }
.Lsgu_uu_2:
	v_lshlrev_b32_e32 v126, 16, v56
	v_and_b32_e32 v56, 0xffff0000, v56
	v_mul_f32_e32 v122, v122, v126
	v_mul_f32_e32 v56, v123, v56
	v_cvt_pk_bf16_f32 v56, v122, v56
	v_lshlrev_b32_e32 v122, 16, v57
	v_add_f32_e32 v123, v120, v124
	v_mul_f32_e32 v122, v123, v122
	v_and_b32_e32 v57, 0xffff0000, v57
	v_add_f32_e32 v123, v120, v125
	v_mul_f32_e32 v57, v123, v57
	v_cvt_pk_bf16_f32 v57, v122, v57
	v_lshlrev_b32_e32 v122, 16, v58
	v_add_f32_e32 v60, v120, v60
	v_and_b32_e32 v58, 0xffff0000, v58
	v_add_f32_e32 v61, v120, v61
	v_mul_f32_e32 v60, v60, v122
	v_mul_f32_e32 v58, v61, v58
	v_cvt_pk_bf16_f32 v58, v60, v58
	v_lshlrev_b32_e32 v60, 16, v59
	v_add_f32_e32 v61, v120, v62
	v_mul_f32_e32 v60, v61, v60
	v_and_b32_e32 v59, 0xffff0000, v59
	v_add_f32_e32 v61, v120, v63
	v_mul_f32_e32 v59, v61, v59
	v_lshl_add_u32 v122, v111, 1, v121
	v_cvt_pk_bf16_f32 v59, v60, v59
	ds_read_b128 v[60:63], v122 offset:17408
	ds_read_b128 v[122:125], v122 offset:18496
	ds_read_b128 v[126:129], v130 offset:17408
	ds_read_b128 v[130:133], v130 offset:18496
	s_waitcnt lgkmcnt(3)
	v_mfma_f32_16x16x32_bf16 v[60:63], v[60:63], v[12:15], 0
	global_store_dwordx4 v[138:139], v[56:59], off offset:1088
	v_lshl_add_u64 v[80:81], v[80:81], 0, s[4:5]
	v_lshl_add_u64 v[90:91], v[90:91], 0, s[70:71]
	s_waitcnt lgkmcnt(2)
	v_mfma_f32_16x16x32_bf16 v[122:125], v[122:125], v[12:15], 0
	s_mov_b32 s4, s1
	s_waitcnt lgkmcnt(1)
	v_mfma_f32_16x16x32_bf16 v[60:63], v[126:129], v[8:11], v[60:63]
	ds_read_b128 v[126:129], v134 offset:17408
	s_waitcnt lgkmcnt(1)
	v_mfma_f32_16x16x32_bf16 v[122:125], v[130:133], v[8:11], v[122:125]
	ds_read_b128 v[130:133], v134 offset:18496
	v_lshl_add_u32 v134, v114, 1, v121
	s_waitcnt lgkmcnt(1)
	v_mfma_f32_16x16x32_bf16 v[60:63], v[126:129], v[4:7], v[60:63]
	ds_read_b128 v[126:129], v134 offset:17408
	s_waitcnt lgkmcnt(1)
	v_mfma_f32_16x16x32_bf16 v[122:125], v[130:133], v[4:7], v[122:125]
	ds_read_b128 v[130:133], v134 offset:18496
	s_waitcnt lgkmcnt(1)
	v_mfma_f32_16x16x32_bf16 v[60:63], v[126:129], v[0:3], v[60:63]
	v_lshl_add_u32 v126, v115, 1, v121
	s_waitcnt lgkmcnt(0)
	v_mfma_f32_16x16x32_bf16 v[56:59], v[130:133], v[0:3], v[122:125]
	s_nop 4
	v_add_f32_e32 v60, v120, v60
	v_add_f32_e32 v61, v120, v61
	s_waitcnt vmcnt(3)
	v_lshlrev_b32_e32 v122, 16, v52
	v_and_b32_e32 v52, 0xffff0000, v52
	v_mul_f32_e32 v60, v60, v122
	v_mul_f32_e32 v52, v61, v52
	v_cvt_pk_bf16_f32 v52, v60, v52
	v_lshlrev_b32_e32 v60, 16, v53
	v_add_f32_e32 v61, v120, v62
	v_mul_f32_e32 v60, v61, v60
	v_and_b32_e32 v53, 0xffff0000, v53
	v_add_f32_e32 v61, v120, v63
	v_mul_f32_e32 v53, v61, v53
	v_cvt_pk_bf16_f32 v53, v60, v53
	v_lshlrev_b32_e32 v60, 16, v54
	v_add_f32_e32 v56, v120, v56
	v_and_b32_e32 v54, 0xffff0000, v54
	v_add_f32_e32 v57, v120, v57
	v_mul_f32_e32 v56, v56, v60
	v_mul_f32_e32 v54, v57, v54
	v_cvt_pk_bf16_f32 v54, v56, v54
	v_lshlrev_b32_e32 v56, 16, v55
	v_add_f32_e32 v57, v120, v58
	v_mul_f32_e32 v56, v57, v56
	v_and_b32_e32 v55, 0xffff0000, v55
	v_add_f32_e32 v57, v120, v59
	v_mul_f32_e32 v55, v57, v55
	v_lshl_add_u32 v60, v102, 1, v121
	v_cvt_pk_bf16_f32 v55, v56, v55
	ds_read_b128 v[56:59], v60 offset:26112
	ds_read_b128 v[60:63], v60 offset:27200
	s_waitcnt lgkmcnt(1)
	v_mfma_f32_16x16x32_bf16 v[56:59], v[56:59], v[12:15], 0
	ds_read_b128 v[122:125], v126 offset:26112
	global_store_dwordx4 v[138:139], v[52:55], off offset:1152
	s_waitcnt lgkmcnt(1)
	v_mfma_f32_16x16x32_bf16 v[12:15], v[60:63], v[12:15], 0
	ds_read_b128 v[60:63], v126 offset:27200
	v_lshl_add_u32 v126, v116, 1, v121
	v_lshl_add_u32 v121, v117, 1, v121
	s_waitcnt lgkmcnt(1)
	v_mfma_f32_16x16x32_bf16 v[56:59], v[122:125], v[8:11], v[56:59]
	ds_read_b128 v[122:125], v126 offset:26112
	s_waitcnt lgkmcnt(1)
	v_mfma_f32_16x16x32_bf16 v[8:11], v[60:63], v[8:11], v[12:15]
	ds_read_b128 v[60:63], v121 offset:26112
	s_nop 1
	ds_read_b128 v[12:15], v126 offset:27200
	s_waitcnt lgkmcnt(2)
	v_mfma_f32_16x16x32_bf16 v[56:59], v[122:125], v[4:7], v[56:59]
	v_mov_b64_e32 v[124:125], v[42:43]
	v_mov_b64_e32 v[122:123], v[40:41]
	s_waitcnt lgkmcnt(0)
	v_mfma_f32_16x16x32_bf16 v[4:7], v[12:15], v[4:7], v[8:11]
	s_nop 2
	ds_read_b128 v[8:11], v121 offset:27200
	v_mov_b64_e32 v[12:13], v[44:45]
	v_mov_b64_e32 v[14:15], v[46:47]
	v_mfma_f32_16x16x32_bf16 v[40:43], v[60:63], v[0:3], v[56:59]
	v_mov_b64_e32 v[62:63], v[38:39]
	v_mov_b64_e32 v[60:61], v[36:37]
	v_mov_b64_e32 v[44:45], v[64:65]
	s_waitcnt lgkmcnt(0)
	v_mfma_f32_16x16x32_bf16 v[0:3], v[8:11], v[0:3], v[4:7]
	v_mov_b64_e32 v[58:59], v[34:35]
	s_waitcnt vmcnt(3)
	s_nop 0
	v_lshlrev_b32_e32 v4, 16, v48
	v_add_f32_e32 v5, v120, v40
	v_mul_f32_e32 v4, v5, v4
	v_and_b32_e32 v5, 0xffff0000, v48
	v_add_f32_e32 v6, v120, v41
	v_mul_f32_e32 v5, v6, v5
	v_cvt_pk_bf16_f32 v4, v4, v5
	v_lshlrev_b32_e32 v5, 16, v49
	v_add_f32_e32 v6, v120, v42
	v_mul_f32_e32 v5, v6, v5
	v_and_b32_e32 v6, 0xffff0000, v49
	v_add_f32_e32 v7, v120, v43
	v_mul_f32_e32 v6, v7, v6
	v_cvt_pk_bf16_f32 v5, v5, v6
	v_lshlrev_b32_e32 v6, 16, v50
	v_add_f32_e32 v0, v120, v0
	v_mul_f32_e32 v0, v0, v6
	v_and_b32_e32 v6, 0xffff0000, v50
	v_add_f32_e32 v1, v120, v1
	v_mul_f32_e32 v1, v1, v6
	v_cvt_pk_bf16_f32 v6, v0, v1
	v_lshlrev_b32_e32 v0, 16, v51
	v_add_f32_e32 v1, v120, v2
	v_mul_f32_e32 v0, v1, v0
	v_and_b32_e32 v1, 0xffff0000, v51
	v_add_f32_e32 v2, v120, v3
	v_mov_b64_e32 v[56:57], v[32:33]
	v_mul_f32_e32 v1, v2, v1
	v_cvt_pk_bf16_f32 v7, v0, v1
	global_store_dwordx4 v[138:139], v[4:7], off offset:1216
	v_mov_b64_e32 v[40:41], v[68:69]
	v_mov_b64_e32 v[32:33], v[72:73]
	v_mov_b64_e32 v[36:37], v[76:77]
	v_mov_b64_e32 v[0:1], v[60:61]
	v_mov_b64_e32 v[4:5], v[56:57]
	v_mov_b64_e32 v[8:9], v[122:123]
	v_mov_b64_e32 v[46:47], v[66:67]
	v_mov_b64_e32 v[42:43], v[70:71]
	v_mov_b64_e32 v[34:35], v[74:75]
	v_mov_b64_e32 v[38:39], v[78:79]
	v_mov_b64_e32 v[2:3], v[62:63]
	v_mov_b64_e32 v[6:7], v[58:59]
	v_mov_b64_e32 v[10:11], v[124:125]
	s_cmpk_lg_i32 s0, 0x1000
	s_barrier
	s_cbranch_scc0 .LBB0_319

; __device__ __forceinline__ float bf_lo(unsigned u) { return __uint_as_float(u << 16); }
; __device__ __forceinline__ float bf_hi(unsigned u) { return __uint_as_float(u & 0xffff0000u); }
;     __device__ __forceinline__ void mid(f32x4 (&acc)[2][2][4][2], const Unit& u, int wr, int wc, int fr, int fq) const {
;         unsigned off = (unsigned)(u.pm * BM + wr * 64 + fr) * 2048u + (unsigned)(u.pn * BM + wc * 32 + 8 * fq);
; #pragma unroll
;         for (int ai = 0; ai < 2; ++ai) {
;             asm volatile("" : "+v"(off) :: "memory");
;             u32x4 sa[4][2], sb[4][2];
; #pragma unroll
;             for (int m = 0; m < 4; ++m)
; #pragma unroll
;                 for (int bj = 0; bj < 2; ++bj) { sa[m][bj] = *(const u32x4*)(sg + off + m * 16 * 2048 + bj * HALF); sb[m][bj] = *(const u32x4*)(sg + off + m * 16 * 2048 + 1024 + bj * HALF); }
; #pragma unroll
;             for (int m = 0; m < 4; ++m)
; #pragma unroll
;                 for (int bj = 0; bj < 2; ++bj) {
;                     const unsigned av[4] = {sa[m][bj].x, sa[m][bj].y, sa[m][bj].z, sa[m][bj].w}, bv[4] = {sb[m][bj].x, sb[m][bj].y, sb[m][bj].z, sb[m][bj].w};
; #pragma unroll
;                     for (int q = 0; q < 4; ++q) { const float r0 = bf_lo(av[q]) * __builtin_amdgcn_rcpf(fmaxf(bf_lo(bv[q]), 1e-30f)), r1 = bf_hi(av[q]) * __builtin_amdgcn_rcpf(fmaxf(bf_hi(bv[q]), 1e-30f));
;                         acc[ai][bj][m][q >> 1][(q & 1) * 2] *= r0; acc[ai][bj][m][q >> 1][(q & 1) * 2 + 1] *= r1; } }
;             off += 128u * 2048u; }
.LBB0_423:
	s_cmpk_lg_i32 s26, 0x400
	s_cbranch_scc1 .LBB0_422
	v_mov_b32_e32 v194, v218
	s_nop 0
	v_lshl_add_u64 v[128:129], v[194:195], 1, s[10:11]
	global_load_dwordx4 v[184:187], v[128:129], off
	global_load_dwordx4 v[188:191], v[128:129], off offset:2048
	global_load_dwordx4 v[176:179], v[128:129], off offset:256
	global_load_dwordx4 v[180:183], v[128:129], off offset:2304
	v_add_co_u32_e32 v130, vcc, s72, v128
	v_add_u32_e32 v194, 0x40000, v194
	s_nop 0
	v_addc_co_u32_e32 v131, vcc, 0, v129, vcc
	global_load_dwordx4 v[168:171], v[130:131], off
	global_load_dwordx4 v[172:175], v[130:131], off offset:2048
	global_load_dwordx4 v[160:163], v[130:131], off offset:256
	global_load_dwordx4 v[164:167], v[130:131], off offset:2304
	v_add_co_u32_e32 v130, vcc, s43, v128
	s_waitcnt vmcnt(7)
	v_lshlrev_b32_e32 v240, 16, v184
	s_waitcnt vmcnt(6)
	v_lshlrev_b32_e32 v219, 16, v188
	v_and_b32_e32 v188, 0xffff0000, v188
	v_and_b32_e32 v241, 0xffff0000, v184
	v_lshlrev_b32_e32 v184, 16, v189
	v_max_f32_e32 v188, v188, v188
	v_max_f32_e32 v184, v184, v184
	v_max_f32_e32 v188, 0xda24260, v188
	v_max_f32_e32 v184, 0xda24260, v184
	v_rcp_f32_e32 v239, v188
	v_rcp_f32_e32 v188, v184
	v_and_b32_e32 v184, 0xffff0000, v189
	v_max_f32_e32 v184, v184, v184
	v_max_f32_e32 v184, 0xda24260, v184
	v_rcp_f32_e32 v189, v184
	v_lshlrev_b32_e32 v184, 16, v185
	v_and_b32_e32 v185, 0xffff0000, v185
	v_addc_co_u32_e32 v131, vcc, 0, v129, vcc
	v_pk_mul_f32 v[184:185], v[188:189], v[184:185]
	v_lshlrev_b32_e32 v188, 16, v186
	v_pk_mul_f32 v[126:127], v[126:127], v[184:185]
	v_lshlrev_b32_e32 v184, 16, v190
	v_and_b32_e32 v185, 0xffff0000, v190
	v_max_f32_e32 v184, v184, v184
	v_max_f32_e32 v185, v185, v185
	v_max_f32_e32 v184, 0xda24260, v184
	v_max_f32_e32 v185, 0xda24260, v185
	v_rcp_f32_e32 v184, v184
	v_rcp_f32_e32 v185, v185
	v_and_b32_e32 v189, 0xffff0000, v186
	v_lshlrev_b32_e32 v186, 16, v187
	v_and_b32_e32 v187, 0xffff0000, v187
	v_pk_mul_f32 v[184:185], v[184:185], v[188:189]
	global_load_dwordx4 v[152:155], v[130:131], off
	global_load_dwordx4 v[156:159], v[130:131], off offset:2048
	global_load_dwordx4 v[144:147], v[130:131], off offset:256
	global_load_dwordx4 v[148:151], v[130:131], off offset:2304
	v_pk_mul_f32 v[120:121], v[120:121], v[184:185]
	v_lshlrev_b32_e32 v184, 16, v191
	v_and_b32_e32 v185, 0xffff0000, v191
	v_max_f32_e32 v184, v184, v184
	v_max_f32_e32 v185, v185, v185
	v_max_f32_e32 v184, 0xda24260, v184
	v_max_f32_e32 v185, 0xda24260, v185
	v_rcp_f32_e32 v184, v184
	v_rcp_f32_e32 v185, v185
	v_add_co_u32_e32 v132, vcc, s60, v128
	v_max_f32_e32 v219, v219, v219
	v_pk_mul_f32 v[184:185], v[184:185], v[186:187]
	s_waitcnt vmcnt(9)
	v_lshlrev_b32_e32 v186, 16, v176
	v_pk_mul_f32 v[122:123], v[122:123], v[184:185]
	s_waitcnt vmcnt(8)
	v_lshlrev_b32_e32 v184, 16, v180
	v_and_b32_e32 v180, 0xffff0000, v180
	v_and_b32_e32 v187, 0xffff0000, v176
	v_lshlrev_b32_e32 v176, 16, v181
	v_max_f32_e32 v180, v180, v180
	v_max_f32_e32 v176, v176, v176
	v_max_f32_e32 v180, 0xda24260, v180
	v_max_f32_e32 v176, 0xda24260, v176
	v_rcp_f32_e32 v185, v180
	v_rcp_f32_e32 v180, v176
	v_and_b32_e32 v176, 0xffff0000, v181
	v_max_f32_e32 v176, v176, v176
	v_max_f32_e32 v176, 0xda24260, v176
	v_rcp_f32_e32 v181, v176
	v_lshlrev_b32_e32 v176, 16, v177
	v_and_b32_e32 v177, 0xffff0000, v177
	v_addc_co_u32_e32 v133, vcc, 0, v129, vcc
	v_pk_mul_f32 v[176:177], v[180:181], v[176:177]
	v_lshlrev_b32_e32 v180, 16, v178
	v_pk_mul_f32 v[118:119], v[118:119], v[176:177]
	v_lshlrev_b32_e32 v176, 16, v182
	v_and_b32_e32 v177, 0xffff0000, v182
	v_max_f32_e32 v176, v176, v176
	v_max_f32_e32 v177, v177, v177
	v_max_f32_e32 v176, 0xda24260, v176
	v_max_f32_e32 v177, 0xda24260, v177
	v_rcp_f32_e32 v176, v176
	v_rcp_f32_e32 v177, v177
	v_and_b32_e32 v181, 0xffff0000, v178
	v_lshlrev_b32_e32 v178, 16, v179
	v_and_b32_e32 v179, 0xffff0000, v179
	v_pk_mul_f32 v[176:177], v[176:177], v[180:181]
	global_load_dwordx4 v[136:139], v[132:133], off
	global_load_dwordx4 v[140:143], v[132:133], off offset:2048
	global_load_dwordx4 v[128:131], v[132:133], off offset:256
	s_nop 0
	global_load_dwordx4 v[132:135], v[132:133], off offset:2304
	v_pk_mul_f32 v[112:113], v[112:113], v[176:177]
	v_lshlrev_b32_e32 v176, 16, v183
	v_and_b32_e32 v177, 0xffff0000, v183
	v_max_f32_e32 v176, v176, v176
	v_max_f32_e32 v177, v177, v177
	v_max_f32_e32 v176, 0xda24260, v176
	v_max_f32_e32 v177, 0xda24260, v177
	v_rcp_f32_e32 v176, v176
	v_rcp_f32_e32 v177, v177
	v_max_f32_e32 v184, v184, v184
	v_max_f32_e32 v184, 0xda24260, v184
	v_pk_mul_f32 v[176:177], v[176:177], v[178:179]
	s_waitcnt vmcnt(11)
	v_lshlrev_b32_e32 v178, 16, v168
	v_pk_mul_f32 v[114:115], v[114:115], v[176:177]
	s_waitcnt vmcnt(10)
	v_lshlrev_b32_e32 v176, 16, v172
	v_and_b32_e32 v172, 0xffff0000, v172
	v_and_b32_e32 v179, 0xffff0000, v168
	v_lshlrev_b32_e32 v168, 16, v173
	v_max_f32_e32 v172, v172, v172
	v_max_f32_e32 v168, v168, v168
	v_max_f32_e32 v172, 0xda24260, v172
	v_max_f32_e32 v168, 0xda24260, v168
	v_rcp_f32_e32 v177, v172
	v_rcp_f32_e32 v172, v168
	v_and_b32_e32 v168, 0xffff0000, v173
	v_max_f32_e32 v168, v168, v168
	v_max_f32_e32 v168, 0xda24260, v168
	v_rcp_f32_e32 v173, v168
	v_lshlrev_b32_e32 v168, 16, v169
	v_and_b32_e32 v169, 0xffff0000, v169
	v_max_f32_e32 v176, v176, v176
	v_pk_mul_f32 v[168:169], v[172:173], v[168:169]
	v_lshlrev_b32_e32 v172, 16, v170
	v_pk_mul_f32 v[110:111], v[110:111], v[168:169]
	v_lshlrev_b32_e32 v168, 16, v174
	v_and_b32_e32 v169, 0xffff0000, v174
	v_max_f32_e32 v168, v168, v168
	v_max_f32_e32 v169, v169, v169
	v_max_f32_e32 v168, 0xda24260, v168
	v_max_f32_e32 v169, 0xda24260, v169
	v_rcp_f32_e32 v168, v168
	v_rcp_f32_e32 v169, v169
	v_and_b32_e32 v173, 0xffff0000, v170
	v_lshlrev_b32_e32 v170, 16, v171
	v_and_b32_e32 v171, 0xffff0000, v171
	v_pk_mul_f32 v[168:169], v[168:169], v[172:173]
	v_max_f32_e32 v176, 0xda24260, v176
	v_pk_mul_f32 v[104:105], v[104:105], v[168:169]
	v_lshlrev_b32_e32 v168, 16, v175
	v_and_b32_e32 v169, 0xffff0000, v175
	v_max_f32_e32 v168, v168, v168
	v_max_f32_e32 v169, v169, v169
	v_max_f32_e32 v168, 0xda24260, v168
	v_max_f32_e32 v169, 0xda24260, v169
	v_rcp_f32_e32 v168, v168
	v_rcp_f32_e32 v169, v169
	v_rcp_f32_e32 v176, v176
	v_rcp_f32_e32 v184, v184
	v_max_f32_e32 v219, 0xda24260, v219
	v_pk_mul_f32 v[168:169], v[168:169], v[170:171]
	s_waitcnt vmcnt(9)
; __device__ __forceinline__ float bf_lo(unsigned u) { return __uint_as_float(u << 16); }
; __device__ __forceinline__ float bf_hi(unsigned u) { return __uint_as_float(u & 0xffff0000u); }
;     __device__ __forceinline__ void mid(f32x4 (&acc)[2][2][4][2], const Unit& u, int wr, int wc, int fr, int fq) const {
;         unsigned off = (unsigned)(u.pm * BM + wr * 64 + fr) * 2048u + (unsigned)(u.pn * BM + wc * 32 + 8 * fq);
; #pragma unroll
;         for (int ai = 0; ai < 2; ++ai) {
;             asm volatile("" : "+v"(off) :: "memory");
;             u32x4 sa[4][2], sb[4][2];
; #pragma unroll
;             for (int m = 0; m < 4; ++m)
; #pragma unroll
;                 for (int bj = 0; bj < 2; ++bj) { sa[m][bj] = *(const u32x4*)(sg + off + m * 16 * 2048 + bj * HALF); sb[m][bj] = *(const u32x4*)(sg + off + m * 16 * 2048 + 1024 + bj * HALF); }
; #pragma unroll
;             for (int m = 0; m < 4; ++m)
; #pragma unroll
;                 for (int bj = 0; bj < 2; ++bj) {
;                     const unsigned av[4] = {sa[m][bj].x, sa[m][bj].y, sa[m][bj].z, sa[m][bj].w}, bv[4] = {sb[m][bj].x, sb[m][bj].y, sb[m][bj].z, sb[m][bj].w};
; #pragma unroll
;                     for (int q = 0; q < 4; ++q) { const float r0 = bf_lo(av[q]) * __builtin_amdgcn_rcpf(fmaxf(bf_lo(bv[q]), 1e-30f)), r1 = bf_hi(av[q]) * __builtin_amdgcn_rcpf(fmaxf(bf_hi(bv[q]), 1e-30f));
;                         acc[ai][bj][m][q >> 1][(q & 1) * 2] *= r0; acc[ai][bj][m][q >> 1][(q & 1) * 2 + 1] *= r1; } }
;             off += 128u * 2048u; }
	v_lshlrev_b32_e32 v170, 16, v160
	v_pk_mul_f32 v[106:107], v[106:107], v[168:169]
	s_waitcnt vmcnt(8)
	v_lshlrev_b32_e32 v168, 16, v164
	v_and_b32_e32 v164, 0xffff0000, v164
	v_and_b32_e32 v171, 0xffff0000, v160
	v_lshlrev_b32_e32 v160, 16, v165
	v_max_f32_e32 v164, v164, v164
	v_max_f32_e32 v160, v160, v160
	v_max_f32_e32 v164, 0xda24260, v164
	v_max_f32_e32 v160, 0xda24260, v160
	v_rcp_f32_e32 v169, v164
	v_rcp_f32_e32 v164, v160
	v_and_b32_e32 v160, 0xffff0000, v165
	v_max_f32_e32 v160, v160, v160
	v_max_f32_e32 v160, 0xda24260, v160
	v_rcp_f32_e32 v165, v160
	v_lshlrev_b32_e32 v160, 16, v161
	v_and_b32_e32 v161, 0xffff0000, v161
	v_pk_mul_f32 v[176:177], v[176:177], v[178:179]
	v_pk_mul_f32 v[160:161], v[164:165], v[160:161]
	v_lshlrev_b32_e32 v164, 16, v162
	v_pk_mul_f32 v[102:103], v[102:103], v[160:161]
	v_lshlrev_b32_e32 v160, 16, v166
	v_and_b32_e32 v161, 0xffff0000, v166
	v_max_f32_e32 v160, v160, v160
	v_max_f32_e32 v161, v161, v161
	v_max_f32_e32 v160, 0xda24260, v160
	v_max_f32_e32 v161, 0xda24260, v161
	v_rcp_f32_e32 v160, v160
	v_rcp_f32_e32 v161, v161
	v_and_b32_e32 v165, 0xffff0000, v162
	v_lshlrev_b32_e32 v162, 16, v163
	v_and_b32_e32 v163, 0xffff0000, v163
	v_pk_mul_f32 v[160:161], v[160:161], v[164:165]
	v_pk_mul_f32 v[108:109], v[108:109], v[176:177]
	v_pk_mul_f32 v[92:93], v[92:93], v[160:161]
	v_lshlrev_b32_e32 v160, 16, v167
	v_and_b32_e32 v161, 0xffff0000, v167
	v_max_f32_e32 v160, v160, v160
	v_max_f32_e32 v161, v161, v161
	v_max_f32_e32 v160, 0xda24260, v160
	v_max_f32_e32 v161, 0xda24260, v161
	v_rcp_f32_e32 v160, v160
	v_rcp_f32_e32 v161, v161
	v_max_f32_e32 v168, v168, v168
	v_max_f32_e32 v168, 0xda24260, v168
	v_rcp_f32_e32 v168, v168
	v_pk_mul_f32 v[160:161], v[160:161], v[162:163]
	s_waitcnt vmcnt(7)
	v_lshlrev_b32_e32 v162, 16, v152
	v_pk_mul_f32 v[94:95], v[94:95], v[160:161]
	s_waitcnt vmcnt(6)
	v_lshlrev_b32_e32 v160, 16, v156
	v_and_b32_e32 v156, 0xffff0000, v156
	v_and_b32_e32 v163, 0xffff0000, v152
	v_lshlrev_b32_e32 v152, 16, v157
	v_max_f32_e32 v156, v156, v156
	v_max_f32_e32 v152, v152, v152
	v_max_f32_e32 v156, 0xda24260, v156
	v_max_f32_e32 v152, 0xda24260, v152
	v_rcp_f32_e32 v161, v156
	v_rcp_f32_e32 v156, v152
	v_and_b32_e32 v152, 0xffff0000, v157
	v_max_f32_e32 v152, v152, v152
	v_max_f32_e32 v152, 0xda24260, v152
	v_rcp_f32_e32 v157, v152
	v_lshlrev_b32_e32 v152, 16, v153
	v_and_b32_e32 v153, 0xffff0000, v153
	v_max_f32_e32 v160, v160, v160
	v_pk_mul_f32 v[152:153], v[156:157], v[152:153]
	v_lshlrev_b32_e32 v156, 16, v154
	v_pk_mul_f32 v[98:99], v[98:99], v[152:153]
	v_lshlrev_b32_e32 v152, 16, v158
	v_and_b32_e32 v153, 0xffff0000, v158
	v_max_f32_e32 v152, v152, v152
	v_max_f32_e32 v153, v153, v153
	v_max_f32_e32 v152, 0xda24260, v152
	v_max_f32_e32 v153, 0xda24260, v153
	v_rcp_f32_e32 v152, v152
	v_rcp_f32_e32 v153, v153
	v_and_b32_e32 v157, 0xffff0000, v154
	v_lshlrev_b32_e32 v154, 16, v155
	v_and_b32_e32 v155, 0xffff0000, v155
	v_pk_mul_f32 v[152:153], v[152:153], v[156:157]
	v_max_f32_e32 v160, 0xda24260, v160
	v_pk_mul_f32 v[88:89], v[88:89], v[152:153]
	v_lshlrev_b32_e32 v152, 16, v159
	v_and_b32_e32 v153, 0xffff0000, v159
	v_max_f32_e32 v152, v152, v152
	v_max_f32_e32 v153, v153, v153
	v_max_f32_e32 v152, 0xda24260, v152
	v_max_f32_e32 v153, 0xda24260, v153
	v_rcp_f32_e32 v152, v152
	v_rcp_f32_e32 v153, v153
	v_rcp_f32_e32 v160, v160
	v_pk_mul_f32 v[184:185], v[184:185], v[186:187]
	v_pk_mul_f32 v[168:169], v[168:169], v[170:171]
	v_pk_mul_f32 v[152:153], v[152:153], v[154:155]
	s_waitcnt vmcnt(5)
	v_lshlrev_b32_e32 v154, 16, v144
	v_pk_mul_f32 v[90:91], v[90:91], v[152:153]
	s_waitcnt vmcnt(4)
	v_lshlrev_b32_e32 v152, 16, v148
	v_and_b32_e32 v148, 0xffff0000, v148
	v_and_b32_e32 v155, 0xffff0000, v144
	v_lshlrev_b32_e32 v144, 16, v149
	v_max_f32_e32 v148, v148, v148
	v_max_f32_e32 v144, v144, v144
	v_max_f32_e32 v148, 0xda24260, v148
	v_max_f32_e32 v144, 0xda24260, v144
	v_rcp_f32_e32 v153, v148
	v_rcp_f32_e32 v148, v144
	v_and_b32_e32 v144, 0xffff0000, v149
	v_max_f32_e32 v144, v144, v144
	v_max_f32_e32 v144, 0xda24260, v144
	v_rcp_f32_e32 v149, v144
	v_lshlrev_b32_e32 v144, 16, v145
	v_and_b32_e32 v145, 0xffff0000, v145
	v_pk_mul_f32 v[160:161], v[160:161], v[162:163]
	v_pk_mul_f32 v[144:145], v[148:149], v[144:145]
	v_lshlrev_b32_e32 v148, 16, v146
	v_pk_mul_f32 v[86:87], v[86:87], v[144:145]
	v_lshlrev_b32_e32 v144, 16, v150
	v_and_b32_e32 v145, 0xffff0000, v150
	v_max_f32_e32 v144, v144, v144
	v_max_f32_e32 v145, v145, v145
	v_max_f32_e32 v144, 0xda24260, v144
	v_max_f32_e32 v145, 0xda24260, v145
	v_rcp_f32_e32 v144, v144
	v_rcp_f32_e32 v145, v145
	v_and_b32_e32 v149, 0xffff0000, v146
	v_lshlrev_b32_e32 v146, 16, v147
	v_and_b32_e32 v147, 0xffff0000, v147
	v_pk_mul_f32 v[144:145], v[144:145], v[148:149]
	v_pk_mul_f32 v[96:97], v[96:97], v[160:161]
	v_pk_mul_f32 v[76:77], v[76:77], v[144:145]
	v_lshlrev_b32_e32 v144, 16, v151
	v_and_b32_e32 v145, 0xffff0000, v151
	v_max_f32_e32 v144, v144, v144
	v_max_f32_e32 v145, v145, v145
	v_max_f32_e32 v144, 0xda24260, v144
	v_max_f32_e32 v145, 0xda24260, v145
	v_rcp_f32_e32 v144, v144
	v_rcp_f32_e32 v145, v145
	v_pk_mul_f32 v[116:117], v[116:117], v[184:185]
	v_pk_mul_f32 v[100:101], v[100:101], v[168:169]
	v_rcp_f32_e32 v238, v219
	v_pk_mul_f32 v[144:145], v[144:145], v[146:147]
	s_waitcnt vmcnt(3)
	v_lshlrev_b32_e32 v146, 16, v136
	v_pk_mul_f32 v[78:79], v[78:79], v[144:145]
	s_waitcnt vmcnt(2)
; __device__ __forceinline__ float bf_lo(unsigned u) { return __uint_as_float(u << 16); }
; __device__ __forceinline__ float bf_hi(unsigned u) { return __uint_as_float(u & 0xffff0000u); }
;     __device__ __forceinline__ void mid(f32x4 (&acc)[2][2][4][2], const Unit& u, int wr, int wc, int fr, int fq) const {
;         unsigned off = (unsigned)(u.pm * BM + wr * 64 + fr) * 2048u + (unsigned)(u.pn * BM + wc * 32 + 8 * fq);
; #pragma unroll
;         for (int ai = 0; ai < 2; ++ai) {
;             asm volatile("" : "+v"(off) :: "memory");
;             u32x4 sa[4][2], sb[4][2];
; #pragma unroll
;             for (int m = 0; m < 4; ++m)
; #pragma unroll
;                 for (int bj = 0; bj < 2; ++bj) { sa[m][bj] = *(const u32x4*)(sg + off + m * 16 * 2048 + bj * HALF); sb[m][bj] = *(const u32x4*)(sg + off + m * 16 * 2048 + 1024 + bj * HALF); }
; #pragma unroll
;             for (int m = 0; m < 4; ++m)
; #pragma unroll
;                 for (int bj = 0; bj < 2; ++bj) {
;                     const unsigned av[4] = {sa[m][bj].x, sa[m][bj].y, sa[m][bj].z, sa[m][bj].w}, bv[4] = {sb[m][bj].x, sb[m][bj].y, sb[m][bj].z, sb[m][bj].w};
; #pragma unroll
;                     for (int q = 0; q < 4; ++q) { const float r0 = bf_lo(av[q]) * __builtin_amdgcn_rcpf(fmaxf(bf_lo(bv[q]), 1e-30f)), r1 = bf_hi(av[q]) * __builtin_amdgcn_rcpf(fmaxf(bf_hi(bv[q]), 1e-30f));
;                         acc[ai][bj][m][q >> 1][(q & 1) * 2] *= r0; acc[ai][bj][m][q >> 1][(q & 1) * 2 + 1] *= r1; } }
;             off += 128u * 2048u; }
	v_lshlrev_b32_e32 v144, 16, v140
	v_and_b32_e32 v140, 0xffff0000, v140
	v_and_b32_e32 v147, 0xffff0000, v136
	v_lshlrev_b32_e32 v136, 16, v141
	v_max_f32_e32 v140, v140, v140
	v_max_f32_e32 v136, v136, v136
	v_max_f32_e32 v140, 0xda24260, v140
	v_max_f32_e32 v136, 0xda24260, v136
	v_rcp_f32_e32 v145, v140
	v_rcp_f32_e32 v140, v136
	v_and_b32_e32 v136, 0xffff0000, v141
	v_max_f32_e32 v136, v136, v136
	v_max_f32_e32 v136, 0xda24260, v136
	v_rcp_f32_e32 v141, v136
	v_lshlrev_b32_e32 v136, 16, v137
	v_and_b32_e32 v137, 0xffff0000, v137
	v_pk_mul_f32 v[238:239], v[238:239], v[240:241]
	v_pk_mul_f32 v[136:137], v[140:141], v[136:137]
	v_lshlrev_b32_e32 v140, 16, v138
	v_pk_mul_f32 v[82:83], v[82:83], v[136:137]
	v_lshlrev_b32_e32 v136, 16, v142
	v_and_b32_e32 v137, 0xffff0000, v142
	v_max_f32_e32 v136, v136, v136
	v_max_f32_e32 v137, v137, v137
	v_max_f32_e32 v136, 0xda24260, v136
	v_max_f32_e32 v137, 0xda24260, v137
	v_rcp_f32_e32 v136, v136
	v_rcp_f32_e32 v137, v137
	v_and_b32_e32 v141, 0xffff0000, v138
	v_lshlrev_b32_e32 v138, 16, v139
	v_and_b32_e32 v139, 0xffff0000, v139
	v_pk_mul_f32 v[136:137], v[136:137], v[140:141]
	v_pk_mul_f32 v[124:125], v[124:125], v[238:239]
	v_pk_mul_f32 v[72:73], v[72:73], v[136:137]
	v_lshlrev_b32_e32 v136, 16, v143
	v_and_b32_e32 v137, 0xffff0000, v143
	v_max_f32_e32 v136, v136, v136
	v_max_f32_e32 v137, v137, v137
	v_max_f32_e32 v136, 0xda24260, v136
	v_max_f32_e32 v137, 0xda24260, v137
	v_rcp_f32_e32 v136, v136
	v_rcp_f32_e32 v137, v137
	v_max_f32_e32 v152, v152, v152
	v_max_f32_e32 v144, v144, v144
	v_max_f32_e32 v152, 0xda24260, v152
	v_pk_mul_f32 v[136:137], v[136:137], v[138:139]
	s_waitcnt vmcnt(1)
	v_lshlrev_b32_e32 v138, 16, v128
	v_pk_mul_f32 v[74:75], v[74:75], v[136:137]
	s_waitcnt vmcnt(0)
	v_lshlrev_b32_e32 v136, 16, v132
	v_and_b32_e32 v132, 0xffff0000, v132
	v_and_b32_e32 v139, 0xffff0000, v128
	v_lshlrev_b32_e32 v128, 16, v133
	v_max_f32_e32 v132, v132, v132
	v_max_f32_e32 v128, v128, v128
	v_max_f32_e32 v132, 0xda24260, v132
	v_max_f32_e32 v128, 0xda24260, v128
	v_rcp_f32_e32 v137, v132
	v_rcp_f32_e32 v132, v128
	v_and_b32_e32 v128, 0xffff0000, v133
	v_max_f32_e32 v128, v128, v128
	v_max_f32_e32 v128, 0xda24260, v128
	v_rcp_f32_e32 v133, v128
	v_lshlrev_b32_e32 v128, 16, v129
	v_and_b32_e32 v129, 0xffff0000, v129
	v_max_f32_e32 v144, 0xda24260, v144
	v_pk_mul_f32 v[128:129], v[132:133], v[128:129]
	v_lshlrev_b32_e32 v132, 16, v130
	v_pk_mul_f32 v[70:71], v[70:71], v[128:129]
	v_lshlrev_b32_e32 v128, 16, v134
	v_and_b32_e32 v129, 0xffff0000, v134
	v_max_f32_e32 v128, v128, v128
	v_max_f32_e32 v129, v129, v129
	v_max_f32_e32 v128, 0xda24260, v128
	v_max_f32_e32 v129, 0xda24260, v129
	v_rcp_f32_e32 v128, v128
	v_rcp_f32_e32 v129, v129
	v_and_b32_e32 v133, 0xffff0000, v130
	v_lshlrev_b32_e32 v130, 16, v131
	v_and_b32_e32 v131, 0xffff0000, v131
	v_pk_mul_f32 v[128:129], v[128:129], v[132:133]
	v_rcp_f32_e32 v152, v152
	v_pk_mul_f32 v[64:65], v[64:65], v[128:129]
	v_lshlrev_b32_e32 v128, 16, v135
	v_and_b32_e32 v129, 0xffff0000, v135
	v_max_f32_e32 v128, v128, v128
	v_max_f32_e32 v129, v129, v129
	v_max_f32_e32 v128, 0xda24260, v128
	v_max_f32_e32 v129, 0xda24260, v129
	v_rcp_f32_e32 v128, v128
	v_rcp_f32_e32 v129, v129
	v_rcp_f32_e32 v144, v144
	v_pk_mul_f32 v[152:153], v[152:153], v[154:155]
	v_max_f32_e32 v136, v136, v136
	v_pk_mul_f32 v[128:129], v[128:129], v[130:131]
	v_pk_mul_f32 v[144:145], v[144:145], v[146:147]
	v_pk_mul_f32 v[66:67], v[66:67], v[128:129]
	v_lshl_add_u64 v[128:129], v[194:195], 1, s[10:11]
	global_load_dwordx4 v[172:175], v[128:129], off
	global_load_dwordx4 v[176:179], v[128:129], off offset:2048
	global_load_dwordx4 v[160:163], v[128:129], off offset:256
	global_load_dwordx4 v[188:191], v[128:129], off offset:2304
	v_add_co_u32_e32 v130, vcc, s72, v128
	v_pk_mul_f32 v[84:85], v[84:85], v[152:153]
	s_nop 0
	v_addc_co_u32_e32 v131, vcc, 0, v129, vcc
	global_load_dwordx4 v[180:183], v[130:131], off
	global_load_dwordx4 v[184:187], v[130:131], off offset:2048
	global_load_dwordx4 v[164:167], v[130:131], off offset:256
	global_load_dwordx4 v[168:171], v[130:131], off offset:2304
	v_add_co_u32_e32 v130, vcc, s43, v128
	v_pk_mul_f32 v[80:81], v[80:81], v[144:145]
	s_nop 0
	v_addc_co_u32_e32 v131, vcc, 0, v129, vcc
	global_load_dwordx4 v[152:155], v[130:131], off
	global_load_dwordx4 v[156:159], v[130:131], off offset:2048
	global_load_dwordx4 v[144:147], v[130:131], off offset:256
	global_load_dwordx4 v[148:151], v[130:131], off offset:2304
	v_max_f32_e32 v136, 0xda24260, v136
	v_rcp_f32_e32 v136, v136
	v_add_co_u32_e32 v132, vcc, s60, v128
	v_pk_mul_f32 v[136:137], v[136:137], v[138:139]
	s_nop 0
	v_addc_co_u32_e32 v133, vcc, 0, v129, vcc
	v_pk_mul_f32 v[68:69], v[68:69], v[136:137]
	global_load_dwordx4 v[136:139], v[132:133], off
	global_load_dwordx4 v[140:143], v[132:133], off offset:2048
	global_load_dwordx4 v[128:131], v[132:133], off offset:256
	s_nop 0
	global_load_dwordx4 v[132:135], v[132:133], off offset:2304
	s_waitcnt vmcnt(15)
	v_lshlrev_b32_e32 v240, 16, v172
	s_waitcnt vmcnt(14)
; __device__ __forceinline__ float bf_lo(unsigned u) { return __uint_as_float(u << 16); }
; __device__ __forceinline__ float bf_hi(unsigned u) { return __uint_as_float(u & 0xffff0000u); }
;     __device__ __forceinline__ void mid(f32x4 (&acc)[2][2][4][2], const Unit& u, int wr, int wc, int fr, int fq) const {
;         unsigned off = (unsigned)(u.pm * BM + wr * 64 + fr) * 2048u + (unsigned)(u.pn * BM + wc * 32 + 8 * fq);
; #pragma unroll
;         for (int ai = 0; ai < 2; ++ai) {
;             asm volatile("" : "+v"(off) :: "memory");
;             u32x4 sa[4][2], sb[4][2];
; #pragma unroll
;             for (int m = 0; m < 4; ++m)
; #pragma unroll
;                 for (int bj = 0; bj < 2; ++bj) { sa[m][bj] = *(const u32x4*)(sg + off + m * 16 * 2048 + bj * HALF); sb[m][bj] = *(const u32x4*)(sg + off + m * 16 * 2048 + 1024 + bj * HALF); }
; #pragma unroll
;             for (int m = 0; m < 4; ++m)
; #pragma unroll
;                 for (int bj = 0; bj < 2; ++bj) {
;                     const unsigned av[4] = {sa[m][bj].x, sa[m][bj].y, sa[m][bj].z, sa[m][bj].w}, bv[4] = {sb[m][bj].x, sb[m][bj].y, sb[m][bj].z, sb[m][bj].w};
; #pragma unroll
;                     for (int q = 0; q < 4; ++q) { const float r0 = bf_lo(av[q]) * __builtin_amdgcn_rcpf(fmaxf(bf_lo(bv[q]), 1e-30f)), r1 = bf_hi(av[q]) * __builtin_amdgcn_rcpf(fmaxf(bf_hi(bv[q]), 1e-30f));
;                         acc[ai][bj][m][q >> 1][(q & 1) * 2] *= r0; acc[ai][bj][m][q >> 1][(q & 1) * 2 + 1] *= r1; } }
;             off += 128u * 2048u; }
	v_lshlrev_b32_e32 v194, 16, v176
	v_and_b32_e32 v176, 0xffff0000, v176
	v_and_b32_e32 v241, 0xffff0000, v172
	v_lshlrev_b32_e32 v172, 16, v177
	v_max_f32_e32 v176, v176, v176
	v_max_f32_e32 v172, v172, v172
	v_max_f32_e32 v176, 0xda24260, v176
	v_max_f32_e32 v172, 0xda24260, v172
	v_rcp_f32_e32 v239, v176
	v_rcp_f32_e32 v176, v172
	v_and_b32_e32 v172, 0xffff0000, v177
	v_max_f32_e32 v172, v172, v172
	v_max_f32_e32 v172, 0xda24260, v172
	v_rcp_f32_e32 v177, v172
	v_lshlrev_b32_e32 v172, 16, v173
	v_and_b32_e32 v173, 0xffff0000, v173
	v_max_f32_e32 v194, v194, v194
	v_pk_mul_f32 v[172:173], v[176:177], v[172:173]
	v_lshlrev_b32_e32 v176, 16, v174
	v_pk_mul_f32 v[62:63], v[62:63], v[172:173]
	v_lshlrev_b32_e32 v172, 16, v178
	v_and_b32_e32 v173, 0xffff0000, v178
	v_max_f32_e32 v172, v172, v172
	v_max_f32_e32 v173, v173, v173
	v_max_f32_e32 v172, 0xda24260, v172
	v_max_f32_e32 v173, 0xda24260, v173
	v_rcp_f32_e32 v172, v172
	v_rcp_f32_e32 v173, v173
	v_and_b32_e32 v177, 0xffff0000, v174
	v_lshlrev_b32_e32 v174, 16, v175
	v_and_b32_e32 v175, 0xffff0000, v175
	v_pk_mul_f32 v[172:173], v[172:173], v[176:177]
	v_max_f32_e32 v194, 0xda24260, v194
	v_pk_mul_f32 v[56:57], v[56:57], v[172:173]
	v_lshlrev_b32_e32 v172, 16, v179
	v_and_b32_e32 v173, 0xffff0000, v179
	v_max_f32_e32 v172, v172, v172
	v_max_f32_e32 v173, v173, v173
	v_max_f32_e32 v172, 0xda24260, v172
	v_max_f32_e32 v173, 0xda24260, v173
	v_rcp_f32_e32 v172, v172
	v_rcp_f32_e32 v173, v173
	v_rcp_f32_e32 v238, v194
	v_pk_mul_f32 v[172:173], v[172:173], v[174:175]
	s_nop 0
	v_pk_mul_f32 v[58:59], v[58:59], v[172:173]
	s_waitcnt vmcnt(12)
	v_lshlrev_b32_e32 v172, 16, v188
	v_and_b32_e32 v173, 0xffff0000, v188
	v_max_f32_e32 v172, v172, v172
	v_max_f32_e32 v173, v173, v173
	v_max_f32_e32 v172, 0xda24260, v172
	v_max_f32_e32 v173, 0xda24260, v173
	v_rcp_f32_e32 v172, v172
	v_rcp_f32_e32 v173, v173
	v_lshlrev_b32_e32 v174, 16, v160
	v_and_b32_e32 v175, 0xffff0000, v160
	v_lshlrev_b32_e32 v160, 16, v189
	v_max_f32_e32 v160, v160, v160
	v_pk_mul_f32 v[172:173], v[172:173], v[174:175]
	v_max_f32_e32 v160, 0xda24260, v160
	v_pk_mul_f32 v[52:53], v[52:53], v[172:173]
	v_rcp_f32_e32 v172, v160
	v_and_b32_e32 v160, 0xffff0000, v189
	v_max_f32_e32 v160, v160, v160
	v_max_f32_e32 v160, 0xda24260, v160
	v_rcp_f32_e32 v173, v160
	v_lshlrev_b32_e32 v160, 16, v161
	v_and_b32_e32 v161, 0xffff0000, v161
	v_pk_mul_f32 v[238:239], v[238:239], v[240:241]
	v_pk_mul_f32 v[160:161], v[172:173], v[160:161]
	v_lshlrev_b32_e32 v172, 16, v162
	v_pk_mul_f32 v[54:55], v[54:55], v[160:161]
	v_lshlrev_b32_e32 v160, 16, v190
	v_and_b32_e32 v161, 0xffff0000, v190
	v_max_f32_e32 v160, v160, v160
	v_max_f32_e32 v161, v161, v161
	v_max_f32_e32 v160, 0xda24260, v160
	v_max_f32_e32 v161, 0xda24260, v161
	v_rcp_f32_e32 v160, v160
	v_rcp_f32_e32 v161, v161
	v_and_b32_e32 v173, 0xffff0000, v162
	v_lshlrev_b32_e32 v162, 16, v163
	v_and_b32_e32 v163, 0xffff0000, v163
	v_pk_mul_f32 v[160:161], v[160:161], v[172:173]
	v_pk_mul_f32 v[60:61], v[60:61], v[238:239]
	v_pk_mul_f32 v[44:45], v[44:45], v[160:161]
	v_lshlrev_b32_e32 v160, 16, v191
	v_and_b32_e32 v161, 0xffff0000, v191
	v_max_f32_e32 v160, v160, v160
	v_max_f32_e32 v161, v161, v161
	v_max_f32_e32 v160, 0xda24260, v160
	v_max_f32_e32 v161, 0xda24260, v161
	v_rcp_f32_e32 v160, v160
	v_rcp_f32_e32 v161, v161
	s_nop 0
	v_pk_mul_f32 v[160:161], v[160:161], v[162:163]
	s_nop 0
	v_pk_mul_f32 v[46:47], v[46:47], v[160:161]
	s_waitcnt vmcnt(10)
	v_lshlrev_b32_e32 v160, 16, v184
	v_and_b32_e32 v161, 0xffff0000, v184
	v_max_f32_e32 v160, v160, v160
	v_max_f32_e32 v161, v161, v161
	v_max_f32_e32 v160, 0xda24260, v160
	v_max_f32_e32 v161, 0xda24260, v161
	v_rcp_f32_e32 v160, v160
	v_rcp_f32_e32 v161, v161
	v_lshlrev_b32_e32 v162, 16, v180
	v_and_b32_e32 v163, 0xffff0000, v180
	v_pk_mul_f32 v[160:161], v[160:161], v[162:163]
	s_nop 0
	v_pk_mul_f32 v[48:49], v[48:49], v[160:161]
	v_lshlrev_b32_e32 v160, 16, v185
	v_and_b32_e32 v161, 0xffff0000, v185
	v_max_f32_e32 v160, v160, v160
	v_max_f32_e32 v161, v161, v161
	v_max_f32_e32 v160, 0xda24260, v160
	v_max_f32_e32 v161, 0xda24260, v161
	v_rcp_f32_e32 v160, v160
	v_rcp_f32_e32 v161, v161
	v_lshlrev_b32_e32 v162, 16, v181
	v_and_b32_e32 v163, 0xffff0000, v181
	v_pk_mul_f32 v[160:161], v[160:161], v[162:163]
	s_nop 0
	v_pk_mul_f32 v[50:51], v[50:51], v[160:161]
	v_lshlrev_b32_e32 v160, 16, v186
	v_and_b32_e32 v161, 0xffff0000, v186
	v_max_f32_e32 v160, v160, v160
	v_max_f32_e32 v161, v161, v161
	v_max_f32_e32 v160, 0xda24260, v160
	v_max_f32_e32 v161, 0xda24260, v161
	v_rcp_f32_e32 v160, v160
	v_rcp_f32_e32 v161, v161
	v_lshlrev_b32_e32 v162, 16, v182
	v_and_b32_e32 v163, 0xffff0000, v182
	v_pk_mul_f32 v[160:161], v[160:161], v[162:163]
	s_nop 0
	v_pk_mul_f32 v[40:41], v[40:41], v[160:161]
	v_lshlrev_b32_e32 v160, 16, v187
	v_and_b32_e32 v161, 0xffff0000, v187
	v_max_f32_e32 v160, v160, v160
	v_max_f32_e32 v161, v161, v161
	v_max_f32_e32 v160, 0xda24260, v160
	v_max_f32_e32 v161, 0xda24260, v161
	v_rcp_f32_e32 v160, v160
	v_rcp_f32_e32 v161, v161
	v_lshlrev_b32_e32 v162, 16, v183
	v_and_b32_e32 v163, 0xffff0000, v183
	v_pk_mul_f32 v[160:161], v[160:161], v[162:163]
	s_nop 0
	v_pk_mul_f32 v[42:43], v[42:43], v[160:161]
	s_waitcnt vmcnt(8)
; __device__ __forceinline__ float bf_lo(unsigned u) { return __uint_as_float(u << 16); }
; __device__ __forceinline__ float bf_hi(unsigned u) { return __uint_as_float(u & 0xffff0000u); }
;     __device__ __forceinline__ void mid(f32x4 (&acc)[2][2][4][2], const Unit& u, int wr, int wc, int fr, int fq) const {
;         unsigned off = (unsigned)(u.pm * BM + wr * 64 + fr) * 2048u + (unsigned)(u.pn * BM + wc * 32 + 8 * fq);
; #pragma unroll
;         for (int ai = 0; ai < 2; ++ai) {
;             asm volatile("" : "+v"(off) :: "memory");
;             u32x4 sa[4][2], sb[4][2];
; #pragma unroll
;             for (int m = 0; m < 4; ++m)
; #pragma unroll
;                 for (int bj = 0; bj < 2; ++bj) { sa[m][bj] = *(const u32x4*)(sg + off + m * 16 * 2048 + bj * HALF); sb[m][bj] = *(const u32x4*)(sg + off + m * 16 * 2048 + 1024 + bj * HALF); }
; #pragma unroll
;             for (int m = 0; m < 4; ++m)
; #pragma unroll
;                 for (int bj = 0; bj < 2; ++bj) {
;                     const unsigned av[4] = {sa[m][bj].x, sa[m][bj].y, sa[m][bj].z, sa[m][bj].w}, bv[4] = {sb[m][bj].x, sb[m][bj].y, sb[m][bj].z, sb[m][bj].w};
; #pragma unroll
;                     for (int q = 0; q < 4; ++q) { const float r0 = bf_lo(av[q]) * __builtin_amdgcn_rcpf(fmaxf(bf_lo(bv[q]), 1e-30f)), r1 = bf_hi(av[q]) * __builtin_amdgcn_rcpf(fmaxf(bf_hi(bv[q]), 1e-30f));
;                         acc[ai][bj][m][q >> 1][(q & 1) * 2] *= r0; acc[ai][bj][m][q >> 1][(q & 1) * 2 + 1] *= r1; } }
;             off += 128u * 2048u; }
	v_lshlrev_b32_e32 v160, 16, v168
	v_and_b32_e32 v161, 0xffff0000, v168
	v_max_f32_e32 v160, v160, v160
	v_max_f32_e32 v161, v161, v161
	v_max_f32_e32 v160, 0xda24260, v160
	v_max_f32_e32 v161, 0xda24260, v161
	v_rcp_f32_e32 v160, v160
	v_rcp_f32_e32 v161, v161
	v_lshlrev_b32_e32 v162, 16, v164
	v_and_b32_e32 v163, 0xffff0000, v164
	v_pk_mul_f32 v[160:161], v[160:161], v[162:163]
	s_nop 0
	v_pk_mul_f32 v[36:37], v[36:37], v[160:161]
	v_lshlrev_b32_e32 v160, 16, v169
	v_and_b32_e32 v161, 0xffff0000, v169
	v_max_f32_e32 v160, v160, v160
	v_max_f32_e32 v161, v161, v161
	v_max_f32_e32 v160, 0xda24260, v160
	v_max_f32_e32 v161, 0xda24260, v161
	v_rcp_f32_e32 v160, v160
	v_rcp_f32_e32 v161, v161
	v_lshlrev_b32_e32 v162, 16, v165
	v_and_b32_e32 v163, 0xffff0000, v165
	v_pk_mul_f32 v[160:161], v[160:161], v[162:163]
	s_nop 0
	v_pk_mul_f32 v[38:39], v[38:39], v[160:161]
	v_lshlrev_b32_e32 v160, 16, v170
	v_and_b32_e32 v161, 0xffff0000, v170
	v_max_f32_e32 v160, v160, v160
	v_max_f32_e32 v161, v161, v161
	v_max_f32_e32 v160, 0xda24260, v160
	v_max_f32_e32 v161, 0xda24260, v161
	v_rcp_f32_e32 v160, v160
	v_rcp_f32_e32 v161, v161
	v_lshlrev_b32_e32 v162, 16, v166
	v_and_b32_e32 v163, 0xffff0000, v166
	v_pk_mul_f32 v[160:161], v[160:161], v[162:163]
	s_nop 0
	v_pk_mul_f32 v[28:29], v[28:29], v[160:161]
	v_lshlrev_b32_e32 v160, 16, v171
	v_and_b32_e32 v161, 0xffff0000, v171
	v_max_f32_e32 v160, v160, v160
	v_max_f32_e32 v161, v161, v161
	v_max_f32_e32 v160, 0xda24260, v160
	v_max_f32_e32 v161, 0xda24260, v161
	v_rcp_f32_e32 v160, v160
	v_rcp_f32_e32 v161, v161
	v_lshlrev_b32_e32 v162, 16, v167
	v_and_b32_e32 v163, 0xffff0000, v167
	v_pk_mul_f32 v[160:161], v[160:161], v[162:163]
	s_nop 0
	v_pk_mul_f32 v[30:31], v[30:31], v[160:161]
	s_waitcnt vmcnt(6)
	v_lshlrev_b32_e32 v160, 16, v156
	v_and_b32_e32 v156, 0xffff0000, v156
	v_lshlrev_b32_e32 v162, 16, v152
	v_and_b32_e32 v163, 0xffff0000, v152
	v_lshlrev_b32_e32 v152, 16, v157
	v_max_f32_e32 v156, v156, v156
	v_max_f32_e32 v152, v152, v152
	v_max_f32_e32 v156, 0xda24260, v156
	v_max_f32_e32 v152, 0xda24260, v152
	v_rcp_f32_e32 v161, v156
	v_rcp_f32_e32 v156, v152
	v_and_b32_e32 v152, 0xffff0000, v157
	v_max_f32_e32 v152, v152, v152
	v_max_f32_e32 v152, 0xda24260, v152
	v_rcp_f32_e32 v157, v152
	v_lshlrev_b32_e32 v152, 16, v153
	v_and_b32_e32 v153, 0xffff0000, v153
	v_max_f32_e32 v160, v160, v160
	v_pk_mul_f32 v[152:153], v[156:157], v[152:153]
	v_lshlrev_b32_e32 v156, 16, v154
	v_pk_mul_f32 v[34:35], v[34:35], v[152:153]
	v_lshlrev_b32_e32 v152, 16, v158
	v_and_b32_e32 v153, 0xffff0000, v158
	v_max_f32_e32 v152, v152, v152
	v_max_f32_e32 v153, v153, v153
	v_max_f32_e32 v152, 0xda24260, v152
	v_max_f32_e32 v153, 0xda24260, v153
	v_rcp_f32_e32 v152, v152
	v_rcp_f32_e32 v153, v153
	v_and_b32_e32 v157, 0xffff0000, v154
	v_lshlrev_b32_e32 v154, 16, v155
	v_and_b32_e32 v155, 0xffff0000, v155
	v_pk_mul_f32 v[152:153], v[152:153], v[156:157]
	v_max_f32_e32 v160, 0xda24260, v160
	v_pk_mul_f32 v[24:25], v[24:25], v[152:153]
	v_lshlrev_b32_e32 v152, 16, v159
	v_and_b32_e32 v153, 0xffff0000, v159
	v_max_f32_e32 v152, v152, v152
	v_max_f32_e32 v153, v153, v153
	v_max_f32_e32 v152, 0xda24260, v152
	v_max_f32_e32 v153, 0xda24260, v153
	v_rcp_f32_e32 v152, v152
	v_rcp_f32_e32 v153, v153
	v_rcp_f32_e32 v160, v160
	v_pk_mul_f32 v[152:153], v[152:153], v[154:155]
	s_nop 0
	v_pk_mul_f32 v[26:27], v[26:27], v[152:153]
	s_waitcnt vmcnt(4)
	v_lshlrev_b32_e32 v152, 16, v148
	v_and_b32_e32 v148, 0xffff0000, v148
	v_lshlrev_b32_e32 v154, 16, v144
	v_and_b32_e32 v155, 0xffff0000, v144
	v_lshlrev_b32_e32 v144, 16, v149
	v_max_f32_e32 v148, v148, v148
	v_max_f32_e32 v144, v144, v144
	v_max_f32_e32 v148, 0xda24260, v148
	v_max_f32_e32 v144, 0xda24260, v144
	v_rcp_f32_e32 v153, v148
	v_rcp_f32_e32 v148, v144
	v_and_b32_e32 v144, 0xffff0000, v149
	v_max_f32_e32 v144, v144, v144
	v_max_f32_e32 v144, 0xda24260, v144
	v_rcp_f32_e32 v149, v144
	v_lshlrev_b32_e32 v144, 16, v145
	v_and_b32_e32 v145, 0xffff0000, v145
	v_max_f32_e32 v152, v152, v152
	v_pk_mul_f32 v[144:145], v[148:149], v[144:145]
	v_lshlrev_b32_e32 v148, 16, v146
	v_pk_mul_f32 v[22:23], v[22:23], v[144:145]
	v_lshlrev_b32_e32 v144, 16, v150
	v_and_b32_e32 v145, 0xffff0000, v150
	v_max_f32_e32 v144, v144, v144
	v_max_f32_e32 v145, v145, v145
	v_max_f32_e32 v144, 0xda24260, v144
	v_max_f32_e32 v145, 0xda24260, v145
	v_rcp_f32_e32 v144, v144
	v_rcp_f32_e32 v145, v145
	v_and_b32_e32 v149, 0xffff0000, v146
	v_lshlrev_b32_e32 v146, 16, v147
	v_and_b32_e32 v147, 0xffff0000, v147
	v_pk_mul_f32 v[144:145], v[144:145], v[148:149]
	v_max_f32_e32 v152, 0xda24260, v152
	v_pk_mul_f32 v[12:13], v[12:13], v[144:145]
	v_lshlrev_b32_e32 v144, 16, v151
	v_and_b32_e32 v145, 0xffff0000, v151
	v_max_f32_e32 v144, v144, v144
	v_max_f32_e32 v145, v145, v145
	v_max_f32_e32 v144, 0xda24260, v144
	v_max_f32_e32 v145, 0xda24260, v145
	v_rcp_f32_e32 v144, v144
	v_rcp_f32_e32 v145, v145
	v_rcp_f32_e32 v152, v152
	v_pk_mul_f32 v[160:161], v[160:161], v[162:163]
	v_pk_mul_f32 v[144:145], v[144:145], v[146:147]
	s_nop 0
	v_pk_mul_f32 v[14:15], v[14:15], v[144:145]
	s_waitcnt vmcnt(2)
; __device__ __forceinline__ float bf_lo(unsigned u) { return __uint_as_float(u << 16); }
; __device__ __forceinline__ float bf_hi(unsigned u) { return __uint_as_float(u & 0xffff0000u); }
;     __device__ __forceinline__ void mid(f32x4 (&acc)[2][2][4][2], const Unit& u, int wr, int wc, int fr, int fq) const {
;     ...
;             for (int m = 0; m < 4; ++m)
; #pragma unroll
;                 for (int bj = 0; bj < 2; ++bj) {
;                     const unsigned av[4] = {sa[m][bj].x, sa[m][bj].y, sa[m][bj].z, sa[m][bj].w}, bv[4] = {sb[m][bj].x, sb[m][bj].y, sb[m][bj].z, sb[m][bj].w};
; #pragma unroll
;                     for (int q = 0; q < 4; ++q) { const float r0 = bf_lo(av[q]) * __builtin_amdgcn_rcpf(fmaxf(bf_lo(bv[q]), 1e-30f)), r1 = bf_hi(av[q]) * __builtin_amdgcn_rcpf(fmaxf(bf_hi(bv[q]), 1e-30f));
;                         acc[ai][bj][m][q >> 1][(q & 1) * 2] *= r0; acc[ai][bj][m][q >> 1][(q & 1) * 2 + 1] *= r1; } }
	v_lshlrev_b32_e32 v144, 16, v140
	v_and_b32_e32 v140, 0xffff0000, v140
	v_lshlrev_b32_e32 v146, 16, v136
	v_and_b32_e32 v147, 0xffff0000, v136
	v_lshlrev_b32_e32 v136, 16, v141
	v_max_f32_e32 v140, v140, v140
	v_max_f32_e32 v136, v136, v136
	v_max_f32_e32 v140, 0xda24260, v140
	v_max_f32_e32 v136, 0xda24260, v136
	v_rcp_f32_e32 v145, v140
	v_rcp_f32_e32 v140, v136
	v_and_b32_e32 v136, 0xffff0000, v141
	v_max_f32_e32 v136, v136, v136
	v_max_f32_e32 v136, 0xda24260, v136
	v_rcp_f32_e32 v141, v136
	v_lshlrev_b32_e32 v136, 16, v137
	v_and_b32_e32 v137, 0xffff0000, v137
	v_max_f32_e32 v144, v144, v144
	v_pk_mul_f32 v[136:137], v[140:141], v[136:137]
	v_lshlrev_b32_e32 v140, 16, v138
	v_pk_mul_f32 v[18:19], v[18:19], v[136:137]
	v_lshlrev_b32_e32 v136, 16, v142
	v_and_b32_e32 v137, 0xffff0000, v142
	v_max_f32_e32 v136, v136, v136
	v_max_f32_e32 v137, v137, v137
	v_max_f32_e32 v136, 0xda24260, v136
	v_max_f32_e32 v137, 0xda24260, v137
	v_rcp_f32_e32 v136, v136
	v_rcp_f32_e32 v137, v137
	v_and_b32_e32 v141, 0xffff0000, v138
	v_lshlrev_b32_e32 v138, 16, v139
	v_and_b32_e32 v139, 0xffff0000, v139
	v_pk_mul_f32 v[136:137], v[136:137], v[140:141]
	v_max_f32_e32 v144, 0xda24260, v144
	v_pk_mul_f32 v[8:9], v[8:9], v[136:137]
	v_lshlrev_b32_e32 v136, 16, v143
	v_and_b32_e32 v137, 0xffff0000, v143
	v_max_f32_e32 v136, v136, v136
	v_max_f32_e32 v137, v137, v137
	v_max_f32_e32 v136, 0xda24260, v136
	v_max_f32_e32 v137, 0xda24260, v137
	v_rcp_f32_e32 v136, v136
	v_rcp_f32_e32 v137, v137
	v_rcp_f32_e32 v144, v144
	v_pk_mul_f32 v[152:153], v[152:153], v[154:155]
	v_pk_mul_f32 v[32:33], v[32:33], v[160:161]
	v_pk_mul_f32 v[136:137], v[136:137], v[138:139]
	s_waitcnt vmcnt(1)
	v_lshlrev_b32_e32 v138, 16, v128
	v_pk_mul_f32 v[10:11], v[10:11], v[136:137]
	s_waitcnt vmcnt(0)
	v_lshlrev_b32_e32 v136, 16, v132
	v_and_b32_e32 v132, 0xffff0000, v132
	v_and_b32_e32 v139, 0xffff0000, v128
	v_lshlrev_b32_e32 v128, 16, v133
	v_max_f32_e32 v132, v132, v132
	v_max_f32_e32 v128, v128, v128
	v_max_f32_e32 v132, 0xda24260, v132
	v_max_f32_e32 v128, 0xda24260, v128
	v_rcp_f32_e32 v137, v132
	v_rcp_f32_e32 v132, v128
	v_and_b32_e32 v128, 0xffff0000, v133
	v_max_f32_e32 v128, v128, v128
	v_max_f32_e32 v128, 0xda24260, v128
	v_rcp_f32_e32 v133, v128
	v_lshlrev_b32_e32 v128, 16, v129
	v_and_b32_e32 v129, 0xffff0000, v129
	v_max_f32_e32 v136, v136, v136
	v_pk_mul_f32 v[128:129], v[132:133], v[128:129]
	v_lshlrev_b32_e32 v132, 16, v130
	v_pk_mul_f32 v[6:7], v[6:7], v[128:129]
	v_lshlrev_b32_e32 v128, 16, v134
	v_and_b32_e32 v129, 0xffff0000, v134
	v_max_f32_e32 v128, v128, v128
	v_max_f32_e32 v129, v129, v129
	v_max_f32_e32 v128, 0xda24260, v128
	v_max_f32_e32 v129, 0xda24260, v129
	v_rcp_f32_e32 v128, v128
	v_rcp_f32_e32 v129, v129
	v_and_b32_e32 v133, 0xffff0000, v130
	v_max_f32_e32 v136, 0xda24260, v136
	v_rcp_f32_e32 v136, v136
	v_pk_mul_f32 v[128:129], v[128:129], v[132:133]
	v_lshlrev_b32_e32 v130, 16, v131
	v_pk_mul_f32 v[0:1], v[0:1], v[128:129]
	v_lshlrev_b32_e32 v128, 16, v135
	v_and_b32_e32 v129, 0xffff0000, v135
	v_max_f32_e32 v128, v128, v128
	v_max_f32_e32 v129, v129, v129
	v_max_f32_e32 v128, 0xda24260, v128
	v_max_f32_e32 v129, 0xda24260, v129
	v_rcp_f32_e32 v128, v128
	v_rcp_f32_e32 v129, v129
	v_and_b32_e32 v131, 0xffff0000, v131
	v_pk_mul_f32 v[144:145], v[144:145], v[146:147]
	v_pk_mul_f32 v[136:137], v[136:137], v[138:139]
	v_pk_mul_f32 v[128:129], v[128:129], v[130:131]
	v_pk_mul_f32 v[20:21], v[20:21], v[152:153]
	v_pk_mul_f32 v[16:17], v[16:17], v[144:145]
	v_pk_mul_f32 v[4:5], v[4:5], v[136:137]
	v_pk_mul_f32 v[2:3], v[2:3], v[128:129]
	s_branch .LBB0_422

; __device__ __forceinline__ unsigned cvt_pk_bf16(float lo, float hi) { unsigned r; asm volatile("v_cvt_pk_bf16_f32 %0, %1, %2" : "=v"(r) : "v"(lo), "v"(hi)); return r; }
; __device__ __forceinline__ float bf_lo(unsigned u) { return __uint_as_float(u << 16); }
; __device__ __forceinline__ float bf_hi(unsigned u) { return __uint_as_float(u & 0xffff0000u); }
;     __device__ __forceinline__ void operator()(const f32x4 (&acc)[2][2][4][2], const Unit& u, int wr, int wc, int fr, int fq) const {
;     ...
;             for (int m = 0; m < 4; ++m)
; #pragma unroll
;                 for (int bj = 0; bj < 2; ++bj) sb[m][bj] = *(const u32x4*)(sg + off + m * 16 * 2048 + 1024 + bj * HALF);
;             const unsigned mo = (off >> 11) * 1024u + (off & 2047u);
; #pragma unroll
;             for (int m = 0; m < 4; ++m)
; #pragma unroll
;                 for (int bj = 0; bj < 2; ++bj) { const u32x4 s = sb[m][bj];
;                     const f32x4 a0 = acc[ai][bj][m][0], a1 = acc[ai][bj][m][1];
;                     u32x4 w; w.x = cvt_pk_bf16(a0[0] * bf_lo(s.x), a0[1] * bf_hi(s.x)); w.y = cvt_pk_bf16(a0[2] * bf_lo(s.y), a0[3] * bf_hi(s.y));
;                     w.z = cvt_pk_bf16(a1[0] * bf_lo(s.z), a1[1] * bf_hi(s.z)); w.w = cvt_pk_bf16(a1[2] * bf_lo(s.w), a1[3] * bf_hi(s.w));
;                     *(u32x4*)(merged + mo + m * 16 * 1024 + bj * HALF) = w; }
.LBB0_427:
	v_mov_b32_e32 v219, v195
	s_mov_b32 s1, 0x8000
	v_lshl_add_u64 v[128:129], v[218:219], 1, s[10:11]
	global_load_dwordx4 v[156:159], v[128:129], off offset:2048
	global_load_dwordx4 v[152:155], v[128:129], off offset:2304
	v_add_co_u32_e32 v130, vcc, 0x10000, v128
	v_lshrrev_b32_e32 v160, 1, v218
	s_nop 0
	v_addc_co_u32_e32 v131, vcc, 0, v129, vcc
	global_load_dwordx4 v[148:151], v[130:131], off offset:2048
	global_load_dwordx4 v[144:147], v[130:131], off offset:2304
	v_add_co_u32_e32 v130, vcc, 0x20000, v128
	v_and_b32_e32 v160, 0x7ffffc00, v160
	s_nop 0
	v_addc_co_u32_e32 v131, vcc, 0, v129, vcc
	global_load_dwordx4 v[140:143], v[130:131], off offset:2048
	global_load_dwordx4 v[136:139], v[130:131], off offset:2304
	v_add_co_u32_e32 v128, vcc, 0x30000, v128
	v_and_b32_e32 v161, 0x7ff, v218
	s_nop 0
	v_addc_co_u32_e32 v129, vcc, 0, v129, vcc
	global_load_dwordx4 v[132:135], v[128:129], off offset:2048
	s_nop 0
	global_load_dwordx4 v[128:131], v[128:129], off offset:2304
	v_add_u32_e32 v194, v160, v161
	s_mov_b32 s0, 0x18000
	s_waitcnt vmcnt(7)
	v_lshlrev_b32_e32 v160, 16, v156
	v_and_b32_e32 v156, 0xffff0000, v156
	v_mul_f32_e32 v124, v124, v160
	v_mul_f32_e32 v125, v125, v156
	v_cvt_pk_bf16_f32 v124, v124, v125
	v_lshlrev_b32_e32 v125, 16, v157
	v_mul_f32_e32 v125, v126, v125
	v_and_b32_e32 v126, 0xffff0000, v157
	v_mul_f32_e32 v126, v127, v126
	v_cvt_pk_bf16_f32 v125, v125, v126
	v_lshlrev_b32_e32 v126, 16, v158
	v_mul_f32_e32 v120, v120, v126
	v_and_b32_e32 v126, 0xffff0000, v158
	v_mul_f32_e32 v121, v121, v126
	v_cvt_pk_bf16_f32 v126, v120, v121
	v_lshlrev_b32_e32 v120, 16, v159
	v_mul_f32_e32 v120, v122, v120
	v_and_b32_e32 v121, 0xffff0000, v159
	s_waitcnt vmcnt(6)
	v_lshlrev_b32_e32 v122, 16, v152
	v_mul_f32_e32 v121, v123, v121
	v_mul_f32_e32 v116, v116, v122
	v_and_b32_e32 v122, 0xffff0000, v152
	v_cvt_pk_bf16_f32 v127, v120, v121
	v_lshl_add_u64 v[120:121], v[194:195], 1, s[12:13]
	v_mul_f32_e32 v117, v117, v122
	global_store_dwordx4 v[120:121], v[124:127], off
	v_cvt_pk_bf16_f32 v116, v116, v117
	v_lshlrev_b32_e32 v117, 16, v153
	v_mul_f32_e32 v117, v118, v117
	v_and_b32_e32 v118, 0xffff0000, v153
	v_mul_f32_e32 v118, v119, v118
	v_cvt_pk_bf16_f32 v117, v117, v118
	v_lshlrev_b32_e32 v118, 16, v154
	v_mul_f32_e32 v112, v112, v118
	v_and_b32_e32 v118, 0xffff0000, v154
	v_mul_f32_e32 v113, v113, v118
	v_cvt_pk_bf16_f32 v118, v112, v113
	v_lshlrev_b32_e32 v112, 16, v155
	v_mul_f32_e32 v112, v114, v112
	v_and_b32_e32 v113, 0xffff0000, v155
	v_mul_f32_e32 v113, v115, v113
	v_cvt_pk_bf16_f32 v119, v112, v113
	s_waitcnt vmcnt(6)
	v_lshlrev_b32_e32 v112, 16, v148
	v_mul_f32_e32 v108, v108, v112
	v_and_b32_e32 v112, 0xffff0000, v148
	v_mul_f32_e32 v109, v109, v112
	global_store_dwordx4 v[120:121], v[116:119], off offset:256
	v_cvt_pk_bf16_f32 v108, v108, v109
	v_lshlrev_b32_e32 v109, 16, v149
	v_mul_f32_e32 v109, v110, v109
	v_and_b32_e32 v110, 0xffff0000, v149
	v_mul_f32_e32 v110, v111, v110
	v_cvt_pk_bf16_f32 v109, v109, v110
	v_lshlrev_b32_e32 v110, 16, v150
	v_mul_f32_e32 v104, v104, v110
	v_and_b32_e32 v110, 0xffff0000, v150
	v_mul_f32_e32 v105, v105, v110
	v_cvt_pk_bf16_f32 v110, v104, v105
	v_lshlrev_b32_e32 v104, 16, v151
	v_mul_f32_e32 v104, v106, v104
	v_and_b32_e32 v105, 0xffff0000, v151
	s_waitcnt vmcnt(6)
	v_lshlrev_b32_e32 v106, 16, v144
	v_mul_f32_e32 v105, v107, v105
	v_cvt_pk_bf16_f32 v111, v104, v105
	v_add_co_u32_e32 v104, vcc, s1, v120
	v_mul_f32_e32 v100, v100, v106
	v_and_b32_e32 v106, 0xffff0000, v144
	v_addc_co_u32_e32 v105, vcc, 0, v121, vcc
	v_mul_f32_e32 v101, v101, v106
	global_store_dwordx4 v[104:105], v[108:111], off
	v_cvt_pk_bf16_f32 v100, v100, v101
	v_lshlrev_b32_e32 v101, 16, v145
	v_mul_f32_e32 v101, v102, v101
	v_and_b32_e32 v102, 0xffff0000, v145
	v_mul_f32_e32 v102, v103, v102
	v_cvt_pk_bf16_f32 v101, v101, v102
	v_lshlrev_b32_e32 v102, 16, v146
	v_mul_f32_e32 v92, v92, v102
	v_and_b32_e32 v102, 0xffff0000, v146
	v_mul_f32_e32 v93, v93, v102
	v_cvt_pk_bf16_f32 v102, v92, v93
	v_lshlrev_b32_e32 v92, 16, v147
	v_and_b32_e32 v93, 0xffff0000, v147
	v_mul_f32_e32 v92, v94, v92
	v_mul_f32_e32 v93, v95, v93
	v_cvt_pk_bf16_f32 v103, v92, v93
	s_waitcnt vmcnt(6)
	v_lshlrev_b32_e32 v92, 16, v140
	v_and_b32_e32 v93, 0xffff0000, v140
	v_mul_f32_e32 v92, v96, v92
	v_mul_f32_e32 v93, v97, v93
	global_store_dwordx4 v[104:105], v[100:103], off offset:256
	v_cvt_pk_bf16_f32 v92, v92, v93
	v_lshlrev_b32_e32 v93, 16, v141
	v_and_b32_e32 v94, 0xffff0000, v141
	v_mul_f32_e32 v93, v98, v93
	v_mul_f32_e32 v94, v99, v94
	v_cvt_pk_bf16_f32 v93, v93, v94
	v_lshlrev_b32_e32 v94, 16, v142
	v_mul_f32_e32 v88, v88, v94
	v_and_b32_e32 v94, 0xffff0000, v142
	v_mul_f32_e32 v89, v89, v94
	v_cvt_pk_bf16_f32 v94, v88, v89
	v_lshlrev_b32_e32 v88, 16, v143
	v_mul_f32_e32 v88, v90, v88
	v_and_b32_e32 v89, 0xffff0000, v143
	s_waitcnt vmcnt(6)
	v_lshlrev_b32_e32 v90, 16, v136
	v_mul_f32_e32 v89, v91, v89
	v_cvt_pk_bf16_f32 v95, v88, v89
	v_add_co_u32_e32 v88, vcc, s72, v120
	v_mul_f32_e32 v84, v84, v90
	v_and_b32_e32 v90, 0xffff0000, v136
	v_addc_co_u32_e32 v89, vcc, 0, v121, vcc
	v_mul_f32_e32 v85, v85, v90
	global_store_dwordx4 v[88:89], v[92:95], off
	v_cvt_pk_bf16_f32 v84, v84, v85
	v_lshlrev_b32_e32 v85, 16, v137
	v_mul_f32_e32 v85, v86, v85
	v_and_b32_e32 v86, 0xffff0000, v137
	v_mul_f32_e32 v86, v87, v86
	v_cvt_pk_bf16_f32 v85, v85, v86
	v_lshlrev_b32_e32 v86, 16, v138
	v_mul_f32_e32 v76, v76, v86
	v_and_b32_e32 v86, 0xffff0000, v138
	v_mul_f32_e32 v77, v77, v86
	v_cvt_pk_bf16_f32 v86, v76, v77
	v_lshlrev_b32_e32 v76, 16, v139
	v_and_b32_e32 v77, 0xffff0000, v139
	v_mul_f32_e32 v76, v78, v76
	v_mul_f32_e32 v77, v79, v77
	v_cvt_pk_bf16_f32 v87, v76, v77
	s_waitcnt vmcnt(6)
; __device__ __forceinline__ unsigned cvt_pk_bf16(float lo, float hi) { unsigned r; asm volatile("v_cvt_pk_bf16_f32 %0, %1, %2" : "=v"(r) : "v"(lo), "v"(hi)); return r; }
; __device__ __forceinline__ float bf_lo(unsigned u) { return __uint_as_float(u << 16); }
; __device__ __forceinline__ float bf_hi(unsigned u) { return __uint_as_float(u & 0xffff0000u); }
;     __device__ __forceinline__ void operator()(const f32x4 (&acc)[2][2][4][2], const Unit& u, int wr, int wc, int fr, int fq) const {
;     ...
;             for (int m = 0; m < 4; ++m)
; #pragma unroll
;                 for (int bj = 0; bj < 2; ++bj) sb[m][bj] = *(const u32x4*)(sg + off + m * 16 * 2048 + 1024 + bj * HALF);
;             const unsigned mo = (off >> 11) * 1024u + (off & 2047u);
; #pragma unroll
;             for (int m = 0; m < 4; ++m)
; #pragma unroll
;                 for (int bj = 0; bj < 2; ++bj) { const u32x4 s = sb[m][bj];
;                     const f32x4 a0 = acc[ai][bj][m][0], a1 = acc[ai][bj][m][1];
;                     u32x4 w; w.x = cvt_pk_bf16(a0[0] * bf_lo(s.x), a0[1] * bf_hi(s.x)); w.y = cvt_pk_bf16(a0[2] * bf_lo(s.y), a0[3] * bf_hi(s.y));
;                     w.z = cvt_pk_bf16(a1[0] * bf_lo(s.z), a1[1] * bf_hi(s.z)); w.w = cvt_pk_bf16(a1[2] * bf_lo(s.w), a1[3] * bf_hi(s.w));
;                     *(u32x4*)(merged + mo + m * 16 * 1024 + bj * HALF) = w; }
;             off += 128u * 2048u; }
	v_lshlrev_b32_e32 v76, 16, v132
	v_and_b32_e32 v77, 0xffff0000, v132
	v_mul_f32_e32 v76, v80, v76
	v_mul_f32_e32 v77, v81, v77
	global_store_dwordx4 v[88:89], v[84:87], off offset:256
	v_cvt_pk_bf16_f32 v76, v76, v77
	v_lshlrev_b32_e32 v77, 16, v133
	v_and_b32_e32 v78, 0xffff0000, v133
	v_mul_f32_e32 v77, v82, v77
	v_mul_f32_e32 v78, v83, v78
	v_cvt_pk_bf16_f32 v77, v77, v78
	v_lshlrev_b32_e32 v78, 16, v134
	v_mul_f32_e32 v72, v72, v78
	v_and_b32_e32 v78, 0xffff0000, v134
	v_mul_f32_e32 v73, v73, v78
	v_cvt_pk_bf16_f32 v78, v72, v73
	v_lshlrev_b32_e32 v72, 16, v135
	v_mul_f32_e32 v72, v74, v72
	v_and_b32_e32 v73, 0xffff0000, v135
	s_waitcnt vmcnt(6)
	v_lshlrev_b32_e32 v74, 16, v128
	v_mul_f32_e32 v73, v75, v73
	v_cvt_pk_bf16_f32 v79, v72, v73
	v_add_co_u32_e32 v72, vcc, s0, v120
	v_mul_f32_e32 v68, v68, v74
	v_and_b32_e32 v74, 0xffff0000, v128
	v_addc_co_u32_e32 v73, vcc, 0, v121, vcc
	v_mul_f32_e32 v69, v69, v74
	global_store_dwordx4 v[72:73], v[76:79], off
	v_cvt_pk_bf16_f32 v68, v68, v69
	v_lshlrev_b32_e32 v69, 16, v129
	v_mul_f32_e32 v69, v70, v69
	v_and_b32_e32 v70, 0xffff0000, v129
	v_mul_f32_e32 v70, v71, v70
	v_cvt_pk_bf16_f32 v69, v69, v70
	v_lshlrev_b32_e32 v70, 16, v130
	v_mul_f32_e32 v64, v64, v70
	v_and_b32_e32 v70, 0xffff0000, v130
	v_mul_f32_e32 v65, v65, v70
	v_cvt_pk_bf16_f32 v70, v64, v65
	v_lshlrev_b32_e32 v64, 16, v131
	v_and_b32_e32 v65, 0xffff0000, v131
	v_mul_f32_e32 v64, v66, v64
	v_mul_f32_e32 v65, v67, v65
	v_cvt_pk_bf16_f32 v71, v64, v65
	global_store_dwordx4 v[72:73], v[68:71], off offset:256
	v_add_u32_e32 v194, 0x40000, v218
	s_nop 0
	v_lshl_add_u64 v[88:89], v[194:195], 1, s[10:11]
	global_load_dwordx4 v[64:67], v[88:89], off offset:2048
	global_load_dwordx4 v[68:71], v[88:89], off offset:2304
	v_add_co_u32_e32 v76, vcc, s72, v88
	v_lshrrev_b32_e32 v96, 1, v194
	s_nop 0
	v_addc_co_u32_e32 v77, vcc, 0, v89, vcc
	global_load_dwordx4 v[72:75], v[76:77], off offset:2048
	s_nop 0
	global_load_dwordx4 v[76:79], v[76:77], off offset:2304
	v_add_co_u32_e32 v84, vcc, s43, v88
	v_and_b32_e32 v96, 0x7ffffc00, v96
	s_nop 0
	v_addc_co_u32_e32 v85, vcc, 0, v89, vcc
	global_load_dwordx4 v[80:83], v[84:85], off offset:2048
	s_nop 0
	global_load_dwordx4 v[84:87], v[84:85], off offset:2304
	v_add_co_u32_e32 v92, vcc, s60, v88
	v_and_b32_e32 v97, 0x7ff, v194
	s_nop 0
	v_addc_co_u32_e32 v93, vcc, 0, v89, vcc
	global_load_dwordx4 v[88:91], v[92:93], off offset:2048
	s_nop 0
	global_load_dwordx4 v[92:95], v[92:93], off offset:2304
	v_add_u32_e32 v194, v96, v97
	s_waitcnt vmcnt(7)
	v_lshlrev_b32_e32 v96, 16, v64
	v_and_b32_e32 v64, 0xffff0000, v64
	v_mul_f32_e32 v60, v60, v96
	v_mul_f32_e32 v61, v61, v64
	v_cvt_pk_bf16_f32 v60, v60, v61
	v_lshlrev_b32_e32 v61, 16, v65
	v_mul_f32_e32 v61, v62, v61
	v_and_b32_e32 v62, 0xffff0000, v65
	v_mul_f32_e32 v62, v63, v62
	v_cvt_pk_bf16_f32 v61, v61, v62
	v_lshlrev_b32_e32 v62, 16, v66
	v_mul_f32_e32 v56, v56, v62
	v_and_b32_e32 v62, 0xffff0000, v66
	v_mul_f32_e32 v57, v57, v62
	v_cvt_pk_bf16_f32 v62, v56, v57
	v_lshlrev_b32_e32 v56, 16, v67
	v_mul_f32_e32 v56, v58, v56
	v_and_b32_e32 v57, 0xffff0000, v67
	s_waitcnt vmcnt(6)
	v_lshlrev_b32_e32 v58, 16, v68
	v_mul_f32_e32 v57, v59, v57
	v_mul_f32_e32 v52, v52, v58
	v_and_b32_e32 v58, 0xffff0000, v68
	v_cvt_pk_bf16_f32 v63, v56, v57
	v_lshl_add_u64 v[56:57], v[194:195], 1, s[12:13]
	v_mul_f32_e32 v53, v53, v58
	global_store_dwordx4 v[56:57], v[60:63], off
	v_cvt_pk_bf16_f32 v52, v52, v53
	v_lshlrev_b32_e32 v53, 16, v69
	v_mul_f32_e32 v53, v54, v53
	v_and_b32_e32 v54, 0xffff0000, v69
	v_mul_f32_e32 v54, v55, v54
	v_cvt_pk_bf16_f32 v53, v53, v54
	v_lshlrev_b32_e32 v54, 16, v70
	v_mul_f32_e32 v44, v44, v54
	v_and_b32_e32 v54, 0xffff0000, v70
	v_mul_f32_e32 v45, v45, v54
	v_cvt_pk_bf16_f32 v54, v44, v45
	v_lshlrev_b32_e32 v44, 16, v71
	v_and_b32_e32 v45, 0xffff0000, v71
	v_mul_f32_e32 v44, v46, v44
	v_mul_f32_e32 v45, v47, v45
	v_cvt_pk_bf16_f32 v55, v44, v45
	s_waitcnt vmcnt(6)
	v_lshlrev_b32_e32 v44, 16, v72
	v_and_b32_e32 v45, 0xffff0000, v72
	v_mul_f32_e32 v44, v48, v44
	v_mul_f32_e32 v45, v49, v45
	global_store_dwordx4 v[56:57], v[52:55], off offset:256
	v_cvt_pk_bf16_f32 v44, v44, v45
	v_lshlrev_b32_e32 v45, 16, v73
	v_and_b32_e32 v46, 0xffff0000, v73
	v_mul_f32_e32 v45, v50, v45
	v_mul_f32_e32 v46, v51, v46
	v_cvt_pk_bf16_f32 v45, v45, v46
	v_lshlrev_b32_e32 v46, 16, v74
	v_mul_f32_e32 v40, v40, v46
	v_and_b32_e32 v46, 0xffff0000, v74
	v_mul_f32_e32 v41, v41, v46
	v_cvt_pk_bf16_f32 v46, v40, v41
	v_lshlrev_b32_e32 v40, 16, v75
	v_mul_f32_e32 v40, v42, v40
	v_and_b32_e32 v41, 0xffff0000, v75
	s_waitcnt vmcnt(6)
; __device__ __forceinline__ unsigned cvt_pk_bf16(float lo, float hi) { unsigned r; asm volatile("v_cvt_pk_bf16_f32 %0, %1, %2" : "=v"(r) : "v"(lo), "v"(hi)); return r; }
; __device__ __forceinline__ float bf_lo(unsigned u) { return __uint_as_float(u << 16); }
; __device__ __forceinline__ float bf_hi(unsigned u) { return __uint_as_float(u & 0xffff0000u); }
;     __device__ __forceinline__ void operator()(const f32x4 (&acc)[2][2][4][2], const Unit& u, int wr, int wc, int fr, int fq) const {
;     ...
;             for (int m = 0; m < 4; ++m)
; #pragma unroll
;                 for (int bj = 0; bj < 2; ++bj) { const u32x4 s = sb[m][bj];
;                     const f32x4 a0 = acc[ai][bj][m][0], a1 = acc[ai][bj][m][1];
;                     u32x4 w; w.x = cvt_pk_bf16(a0[0] * bf_lo(s.x), a0[1] * bf_hi(s.x)); w.y = cvt_pk_bf16(a0[2] * bf_lo(s.y), a0[3] * bf_hi(s.y));
;                     w.z = cvt_pk_bf16(a1[0] * bf_lo(s.z), a1[1] * bf_hi(s.z)); w.w = cvt_pk_bf16(a1[2] * bf_lo(s.w), a1[3] * bf_hi(s.w));
;                     *(u32x4*)(merged + mo + m * 16 * 1024 + bj * HALF) = w; }
	v_lshlrev_b32_e32 v42, 16, v76
	v_mul_f32_e32 v41, v43, v41
	v_cvt_pk_bf16_f32 v47, v40, v41
	v_add_co_u32_e32 v40, vcc, s1, v56
	v_mul_f32_e32 v36, v36, v42
	v_and_b32_e32 v42, 0xffff0000, v76
	v_addc_co_u32_e32 v41, vcc, 0, v57, vcc
	v_mul_f32_e32 v37, v37, v42
	global_store_dwordx4 v[40:41], v[44:47], off
	v_cvt_pk_bf16_f32 v36, v36, v37
	v_lshlrev_b32_e32 v37, 16, v77
	v_mul_f32_e32 v37, v38, v37
	v_and_b32_e32 v38, 0xffff0000, v77
	v_mul_f32_e32 v38, v39, v38
	v_cvt_pk_bf16_f32 v37, v37, v38
	v_lshlrev_b32_e32 v38, 16, v78
	v_mul_f32_e32 v28, v28, v38
	v_and_b32_e32 v38, 0xffff0000, v78
	v_mul_f32_e32 v29, v29, v38
	v_cvt_pk_bf16_f32 v38, v28, v29
	v_lshlrev_b32_e32 v28, 16, v79
	v_and_b32_e32 v29, 0xffff0000, v79
	v_mul_f32_e32 v28, v30, v28
	v_mul_f32_e32 v29, v31, v29
	v_cvt_pk_bf16_f32 v39, v28, v29
	s_waitcnt vmcnt(6)
	v_lshlrev_b32_e32 v28, 16, v80
	v_and_b32_e32 v29, 0xffff0000, v80
	v_mul_f32_e32 v28, v32, v28
	v_mul_f32_e32 v29, v33, v29
	global_store_dwordx4 v[40:41], v[36:39], off offset:256
	v_cvt_pk_bf16_f32 v28, v28, v29
	v_lshlrev_b32_e32 v29, 16, v81
	v_and_b32_e32 v30, 0xffff0000, v81
	v_mul_f32_e32 v29, v34, v29
	v_mul_f32_e32 v30, v35, v30
	v_cvt_pk_bf16_f32 v29, v29, v30
	v_lshlrev_b32_e32 v30, 16, v82
	v_mul_f32_e32 v24, v24, v30
	v_and_b32_e32 v30, 0xffff0000, v82
	v_mul_f32_e32 v25, v25, v30
	v_cvt_pk_bf16_f32 v30, v24, v25
	v_lshlrev_b32_e32 v24, 16, v83
	v_mul_f32_e32 v24, v26, v24
	v_and_b32_e32 v25, 0xffff0000, v83
	s_waitcnt vmcnt(6)
	v_lshlrev_b32_e32 v26, 16, v84
	v_mul_f32_e32 v25, v27, v25
	v_cvt_pk_bf16_f32 v31, v24, v25
	v_add_co_u32_e32 v24, vcc, s72, v56
	v_mul_f32_e32 v20, v20, v26
	v_and_b32_e32 v26, 0xffff0000, v84
	v_addc_co_u32_e32 v25, vcc, 0, v57, vcc
	v_mul_f32_e32 v21, v21, v26
	global_store_dwordx4 v[24:25], v[28:31], off
	v_cvt_pk_bf16_f32 v20, v20, v21
	v_lshlrev_b32_e32 v21, 16, v85
	v_mul_f32_e32 v21, v22, v21
	v_and_b32_e32 v22, 0xffff0000, v85
	v_mul_f32_e32 v22, v23, v22
	v_cvt_pk_bf16_f32 v21, v21, v22
	v_lshlrev_b32_e32 v22, 16, v86
	v_mul_f32_e32 v12, v12, v22
	v_and_b32_e32 v22, 0xffff0000, v86
	v_mul_f32_e32 v13, v13, v22
	v_cvt_pk_bf16_f32 v22, v12, v13
	v_lshlrev_b32_e32 v12, 16, v87
	v_and_b32_e32 v13, 0xffff0000, v87
	v_mul_f32_e32 v12, v14, v12
	v_mul_f32_e32 v13, v15, v13
	v_cvt_pk_bf16_f32 v23, v12, v13
	s_waitcnt vmcnt(6)
	v_lshlrev_b32_e32 v12, 16, v88
	v_and_b32_e32 v13, 0xffff0000, v88
	v_mul_f32_e32 v12, v16, v12
	v_mul_f32_e32 v13, v17, v13
	global_store_dwordx4 v[24:25], v[20:23], off offset:256
	v_cvt_pk_bf16_f32 v12, v12, v13
	v_lshlrev_b32_e32 v13, 16, v89
	v_and_b32_e32 v14, 0xffff0000, v89
	v_mul_f32_e32 v13, v18, v13
	v_mul_f32_e32 v14, v19, v14
	v_cvt_pk_bf16_f32 v13, v13, v14
	v_lshlrev_b32_e32 v14, 16, v90
	v_mul_f32_e32 v8, v8, v14
	v_and_b32_e32 v14, 0xffff0000, v90
	v_mul_f32_e32 v9, v9, v14
	v_cvt_pk_bf16_f32 v14, v8, v9
	v_lshlrev_b32_e32 v8, 16, v91
	v_mul_f32_e32 v8, v10, v8
	v_and_b32_e32 v9, 0xffff0000, v91
	s_waitcnt vmcnt(6)
	v_lshlrev_b32_e32 v10, 16, v92
	v_mul_f32_e32 v9, v11, v9
	v_cvt_pk_bf16_f32 v15, v8, v9
	v_add_co_u32_e32 v8, vcc, s0, v56
	v_mul_f32_e32 v4, v4, v10
	v_and_b32_e32 v10, 0xffff0000, v92
	v_addc_co_u32_e32 v9, vcc, 0, v57, vcc
	v_mul_f32_e32 v5, v5, v10
	global_store_dwordx4 v[8:9], v[12:15], off
	v_cvt_pk_bf16_f32 v4, v4, v5
	v_lshlrev_b32_e32 v5, 16, v93
	v_mul_f32_e32 v5, v6, v5
	v_and_b32_e32 v6, 0xffff0000, v93
	v_mul_f32_e32 v6, v7, v6
	v_cvt_pk_bf16_f32 v5, v5, v6
	v_lshlrev_b32_e32 v6, 16, v94
	v_mul_f32_e32 v0, v0, v6
	v_and_b32_e32 v6, 0xffff0000, v94
	v_mul_f32_e32 v1, v1, v6
	v_cvt_pk_bf16_f32 v6, v0, v1
	v_lshlrev_b32_e32 v0, 16, v95
	v_and_b32_e32 v1, 0xffff0000, v95
	s_mov_b64 s[0:1], -1
	s_andn2_b64 vcc, exec, s[6:7]
	v_mul_f32_e32 v0, v2, v0
	v_mul_f32_e32 v1, v3, v1
	v_cvt_pk_bf16_f32 v7, v0, v1
	global_store_dwordx4 v[8:9], v[4:7], off offset:256
	s_cbranch_vccnz .LBB0_414
	s_andn2_b64 vcc, exec, s[8:9]
	s_cbranch_vccnz .LBB0_413
	s_barrier
	s_branch .LBB0_413
